# compact hand-written in-projection epilogues for all remaining tile kinds (q rotary, k|v with LDS-transposed V^T store, gelu(v_b) with LDS-transposed store + LayerNorm row sums): the branchy compiler
# speedup vs baseline: 1.0116x; 1.0116x over previous
.LBB0_123:
	s_cmp_eq_u32 s17, 0
	s_cbranch_scc0 .Lfe_chk
	s_cmp_lt_u32 s35, 4
	s_cbranch_scc1 .Lfe_ua
	s_and_b32 s0, s35, -4
	s_cmp_eq_u32 s0, 20
	s_cbranch_scc1 .Lfe_q
	s_cmp_eq_u32 s35, 24
	s_cbranch_scc1 .Lfe_kv
	s_branch .Lfe_slow
.Lfe_chk:
	s_cmp_eq_u32 s17, 2
	s_cbranch_scc0 .Lfe_fast
	s_cmp_lt_u32 s35, 12
	s_cbranch_scc1 .Lfe_fast
	s_branch .Lfe_vb

.Lfe_q:
	s_lshl_b32 s19, s42, 8
	s_add_i32 s19, s19, s71
	v_or_b32_e32 v162, s19, v147
	v_lshl_or_b32 v130, s35, 8, v174
	s_movk_i32 s27, 0x6a00
	ds_read_b32 v176, v172
	ds_read_b32 v178, v172 offset:64
	ds_read_b32 v180, v172 offset:128
	ds_read_b32 v182, v172 offset:192
	ds_read_b32 v184, v172 offset:512
	ds_read_b32 v186, v172 offset:576
	ds_read_b32 v188, v172 offset:640
	ds_read_b32 v190, v172 offset:704
	v_mul_u32_u24_e32 v165, s27, v162
	v_readlane_b32 s34, v251, 14
	v_readlane_b32 s35, v251, 15
	v_lshl_add_u32 v165, v130, 1, v165
	v_xor_b32_e32 v167, 16, v217
	v_lshlrev_b32_e32 v167, 2, v167
	v_add_u32_e32 v168, 0x20440, v170
	s_mov_b32 s28, 0x3e000000
	s_waitcnt lgkmcnt(0)
	v_pk_mul_f32 v[126:127], v[126:127], v[176:177] op_sel_hi:[1,0]
	v_pk_mul_f32 v[128:129], v[128:129], v[176:177] op_sel_hi:[1,0]
	v_pk_mul_f32 v[122:123], v[122:123], v[176:177] op_sel_hi:[1,0]
	v_pk_mul_f32 v[124:125], v[124:125], v[176:177] op_sel_hi:[1,0]
	v_pk_mul_f32 v[118:119], v[118:119], v[176:177] op_sel_hi:[1,0]
	v_pk_mul_f32 v[120:121], v[120:121], v[176:177] op_sel_hi:[1,0]
	v_pk_mul_f32 v[114:115], v[114:115], v[176:177] op_sel_hi:[1,0]
	v_pk_mul_f32 v[116:117], v[116:117], v[176:177] op_sel_hi:[1,0]
	s_and_saveexec_b64 s[0:1], s[14:15]
	s_cbranch_execz .Lfe_q_nr0
	ds_read_b128 v[232:235], v168 offset:0
	ds_read_b128 v[236:239], v168 offset:16
	ds_read_b128 v[240:243], v168 offset:32
	ds_read_b128 v[244:247], v168 offset:48
	s_mov_b64 exec, s[0:1]
	ds_bpermute_b32 v154, v167, v126
	ds_bpermute_b32 v155, v167, v127
	ds_bpermute_b32 v156, v167, v128
	ds_bpermute_b32 v157, v167, v129
	ds_bpermute_b32 v158, v167, v122
	ds_bpermute_b32 v159, v167, v123
	ds_bpermute_b32 v160, v167, v124
	ds_bpermute_b32 v161, v167, v125
	s_and_b64 exec, exec, s[14:15]
	s_waitcnt lgkmcnt(8)
	v_cndmask_b32_e64 v233, v233, -v233, s[38:39]
	v_cndmask_b32_e64 v235, v235, -v235, s[38:39]
	v_cndmask_b32_e64 v237, v237, -v237, s[38:39]
	v_cndmask_b32_e64 v239, v239, -v239, s[38:39]
	v_cndmask_b32_e64 v241, v241, -v241, s[38:39]
	v_cndmask_b32_e64 v243, v243, -v243, s[38:39]
	v_cndmask_b32_e64 v245, v245, -v245, s[38:39]
	v_cndmask_b32_e64 v247, v247, -v247, s[38:39]
	s_waitcnt lgkmcnt(0)
	v_mul_f32_e32 v224, v154, v233
	v_mul_f32_e32 v225, v155, v235
	v_mul_f32_e32 v226, v156, v237
	v_mul_f32_e32 v227, v157, v239
	v_mul_f32_e32 v228, v158, v241
	v_mul_f32_e32 v229, v159, v243
	v_mul_f32_e32 v230, v160, v245
	v_mul_f32_e32 v231, v161, v247
	v_fma_f32 v126, v126, v232, v224
	v_fma_f32 v127, v127, v234, v225
	v_fma_f32 v128, v128, v236, v226
	v_fma_f32 v129, v129, v238, v227
	v_fma_f32 v122, v122, v240, v228
	v_fma_f32 v123, v123, v242, v229
	v_fma_f32 v124, v124, v244, v230
	v_fma_f32 v125, v125, v246, v231
	s_mov_b64 exec, s[0:1]
	ds_bpermute_b32 v154, v167, v118
	ds_bpermute_b32 v155, v167, v119
	ds_bpermute_b32 v156, v167, v120
	ds_bpermute_b32 v157, v167, v121
	ds_bpermute_b32 v158, v167, v114
	ds_bpermute_b32 v159, v167, v115
	ds_bpermute_b32 v160, v167, v116
	ds_bpermute_b32 v161, v167, v117
	s_and_b64 exec, exec, s[14:15]
	s_waitcnt lgkmcnt(0)
	v_mul_f32_e32 v224, v154, v233
	v_mul_f32_e32 v225, v155, v235
	v_mul_f32_e32 v226, v156, v237
	v_mul_f32_e32 v227, v157, v239
	v_mul_f32_e32 v228, v158, v241
	v_mul_f32_e32 v229, v159, v243
	v_mul_f32_e32 v230, v160, v245
	v_mul_f32_e32 v231, v161, v247
	v_fma_f32 v118, v118, v232, v224
	v_fma_f32 v119, v119, v234, v225
	v_fma_f32 v120, v120, v236, v226
	v_fma_f32 v121, v121, v238, v227
	v_fma_f32 v114, v114, v240, v228
	v_fma_f32 v115, v115, v242, v229
	v_fma_f32 v116, v116, v244, v230
	v_fma_f32 v117, v117, v246, v231
.Lfe_q_nr0:
	s_or_b64 exec, exec, s[0:1]
	v_pk_mul_f32 v[126:127], v[126:127], s[28:29] op_sel_hi:[1,0]
	v_pk_mul_f32 v[128:129], v[128:129], s[28:29] op_sel_hi:[1,0]
	v_pk_mul_f32 v[122:123], v[122:123], s[28:29] op_sel_hi:[1,0]
	v_pk_mul_f32 v[124:125], v[124:125], s[28:29] op_sel_hi:[1,0]
	v_cvt_pk_bf16_f32 v130, v126, v127
	v_cvt_pk_bf16_f32 v131, v128, v129
	v_cvt_pk_bf16_f32 v132, v122, v123
	v_cvt_pk_bf16_f32 v133, v124, v125
	global_store_dwordx4 v165, v[130:133], s[34:35] nt
	v_pk_mul_f32 v[118:119], v[118:119], s[28:29] op_sel_hi:[1,0]
	v_pk_mul_f32 v[120:121], v[120:121], s[28:29] op_sel_hi:[1,0]
	v_pk_mul_f32 v[114:115], v[114:115], s[28:29] op_sel_hi:[1,0]
	v_pk_mul_f32 v[116:117], v[116:117], s[28:29] op_sel_hi:[1,0]
	v_cvt_pk_bf16_f32 v134, v118, v119
	v_cvt_pk_bf16_f32 v135, v120, v121
	v_cvt_pk_bf16_f32 v136, v114, v115
	v_cvt_pk_bf16_f32 v137, v116, v117
	global_store_dwordx4 v165, v[134:137], s[34:35] offset:256 nt
	v_add_u32_e32 v166, 0x6a000, v165
	v_pk_mul_f32 v[110:111], v[110:111], v[178:179] op_sel_hi:[1,0]
	v_pk_mul_f32 v[112:113], v[112:113], v[178:179] op_sel_hi:[1,0]
	v_pk_mul_f32 v[106:107], v[106:107], v[178:179] op_sel_hi:[1,0]
	v_pk_mul_f32 v[108:109], v[108:109], v[178:179] op_sel_hi:[1,0]
	v_pk_mul_f32 v[102:103], v[102:103], v[178:179] op_sel_hi:[1,0]
	v_pk_mul_f32 v[104:105], v[104:105], v[178:179] op_sel_hi:[1,0]
	v_pk_mul_f32 v[98:99], v[98:99], v[178:179] op_sel_hi:[1,0]
	v_pk_mul_f32 v[100:101], v[100:101], v[178:179] op_sel_hi:[1,0]
	s_and_saveexec_b64 s[0:1], s[14:15]
	s_cbranch_execz .Lfe_q_nr1
	ds_read_b128 v[232:235], v168 offset:1024
	ds_read_b128 v[236:239], v168 offset:1040
	ds_read_b128 v[240:243], v168 offset:1056
	ds_read_b128 v[244:247], v168 offset:1072
	s_mov_b64 exec, s[0:1]
	ds_bpermute_b32 v154, v167, v110
	ds_bpermute_b32 v155, v167, v111
	ds_bpermute_b32 v156, v167, v112
	ds_bpermute_b32 v157, v167, v113
	ds_bpermute_b32 v158, v167, v106
	ds_bpermute_b32 v159, v167, v107
	ds_bpermute_b32 v160, v167, v108
	ds_bpermute_b32 v161, v167, v109
	s_and_b64 exec, exec, s[14:15]
	s_waitcnt lgkmcnt(8)
	v_cndmask_b32_e64 v233, v233, -v233, s[38:39]
	v_cndmask_b32_e64 v235, v235, -v235, s[38:39]
	v_cndmask_b32_e64 v237, v237, -v237, s[38:39]
	v_cndmask_b32_e64 v239, v239, -v239, s[38:39]
	v_cndmask_b32_e64 v241, v241, -v241, s[38:39]
	v_cndmask_b32_e64 v243, v243, -v243, s[38:39]
	v_cndmask_b32_e64 v245, v245, -v245, s[38:39]
	v_cndmask_b32_e64 v247, v247, -v247, s[38:39]
	s_waitcnt lgkmcnt(0)
	v_mul_f32_e32 v224, v154, v233
	v_mul_f32_e32 v225, v155, v235
	v_mul_f32_e32 v226, v156, v237
	v_mul_f32_e32 v227, v157, v239
	v_mul_f32_e32 v228, v158, v241
	v_mul_f32_e32 v229, v159, v243
	v_mul_f32_e32 v230, v160, v245
	v_mul_f32_e32 v231, v161, v247
	v_fma_f32 v110, v110, v232, v224
	v_fma_f32 v111, v111, v234, v225
	v_fma_f32 v112, v112, v236, v226
	v_fma_f32 v113, v113, v238, v227
	v_fma_f32 v106, v106, v240, v228
	v_fma_f32 v107, v107, v242, v229
	v_fma_f32 v108, v108, v244, v230
	v_fma_f32 v109, v109, v246, v231
	s_mov_b64 exec, s[0:1]
	ds_bpermute_b32 v154, v167, v102
	ds_bpermute_b32 v155, v167, v103
	ds_bpermute_b32 v156, v167, v104
	ds_bpermute_b32 v157, v167, v105
	ds_bpermute_b32 v158, v167, v98
	ds_bpermute_b32 v159, v167, v99
	ds_bpermute_b32 v160, v167, v100
	ds_bpermute_b32 v161, v167, v101
	s_and_b64 exec, exec, s[14:15]
	s_waitcnt lgkmcnt(0)
	v_mul_f32_e32 v224, v154, v233
	v_mul_f32_e32 v225, v155, v235
	v_mul_f32_e32 v226, v156, v237
	v_mul_f32_e32 v227, v157, v239
	v_mul_f32_e32 v228, v158, v241
	v_mul_f32_e32 v229, v159, v243
	v_mul_f32_e32 v230, v160, v245
	v_mul_f32_e32 v231, v161, v247
	v_fma_f32 v102, v102, v232, v224
	v_fma_f32 v103, v103, v234, v225
	v_fma_f32 v104, v104, v236, v226
	v_fma_f32 v105, v105, v238, v227
	v_fma_f32 v98, v98, v240, v228
	v_fma_f32 v99, v99, v242, v229
	v_fma_f32 v100, v100, v244, v230
	v_fma_f32 v101, v101, v246, v231
.Lfe_q_nr1:
	s_or_b64 exec, exec, s[0:1]
	v_pk_mul_f32 v[110:111], v[110:111], s[28:29] op_sel_hi:[1,0]
	v_pk_mul_f32 v[112:113], v[112:113], s[28:29] op_sel_hi:[1,0]
	v_pk_mul_f32 v[106:107], v[106:107], s[28:29] op_sel_hi:[1,0]
	v_pk_mul_f32 v[108:109], v[108:109], s[28:29] op_sel_hi:[1,0]
	v_cvt_pk_bf16_f32 v130, v110, v111
	v_cvt_pk_bf16_f32 v131, v112, v113
	v_cvt_pk_bf16_f32 v132, v106, v107
	v_cvt_pk_bf16_f32 v133, v108, v109
	global_store_dwordx4 v166, v[130:133], s[34:35] nt
	v_pk_mul_f32 v[102:103], v[102:103], s[28:29] op_sel_hi:[1,0]
	v_pk_mul_f32 v[104:105], v[104:105], s[28:29] op_sel_hi:[1,0]
	v_pk_mul_f32 v[98:99], v[98:99], s[28:29] op_sel_hi:[1,0]
	v_pk_mul_f32 v[100:101], v[100:101], s[28:29] op_sel_hi:[1,0]
	v_cvt_pk_bf16_f32 v134, v102, v103
	v_cvt_pk_bf16_f32 v135, v104, v105
	v_cvt_pk_bf16_f32 v136, v98, v99
	v_cvt_pk_bf16_f32 v137, v100, v101
	global_store_dwordx4 v166, v[134:137], s[34:35] offset:256 nt
	v_add_u32_e32 v164, 0xd4000, v165
	v_pk_mul_f32 v[94:95], v[94:95], v[180:181] op_sel_hi:[1,0]
	v_pk_mul_f32 v[96:97], v[96:97], v[180:181] op_sel_hi:[1,0]
	v_pk_mul_f32 v[90:91], v[90:91], v[180:181] op_sel_hi:[1,0]
	v_pk_mul_f32 v[92:93], v[92:93], v[180:181] op_sel_hi:[1,0]
	v_pk_mul_f32 v[86:87], v[86:87], v[180:181] op_sel_hi:[1,0]
	v_pk_mul_f32 v[88:89], v[88:89], v[180:181] op_sel_hi:[1,0]
	v_pk_mul_f32 v[82:83], v[82:83], v[180:181] op_sel_hi:[1,0]
	v_pk_mul_f32 v[84:85], v[84:85], v[180:181] op_sel_hi:[1,0]
	s_and_saveexec_b64 s[0:1], s[14:15]
	s_cbranch_execz .Lfe_q_nr2
	ds_read_b128 v[232:235], v168 offset:2048
	ds_read_b128 v[236:239], v168 offset:2064
	ds_read_b128 v[240:243], v168 offset:2080
	ds_read_b128 v[244:247], v168 offset:2096
	s_mov_b64 exec, s[0:1]
	ds_bpermute_b32 v154, v167, v94
	ds_bpermute_b32 v155, v167, v95
	ds_bpermute_b32 v156, v167, v96
	ds_bpermute_b32 v157, v167, v97
	ds_bpermute_b32 v158, v167, v90
	ds_bpermute_b32 v159, v167, v91
	ds_bpermute_b32 v160, v167, v92
	ds_bpermute_b32 v161, v167, v93
	s_and_b64 exec, exec, s[14:15]
	s_waitcnt lgkmcnt(8)
	v_cndmask_b32_e64 v233, v233, -v233, s[38:39]
	v_cndmask_b32_e64 v235, v235, -v235, s[38:39]
	v_cndmask_b32_e64 v237, v237, -v237, s[38:39]
	v_cndmask_b32_e64 v239, v239, -v239, s[38:39]
	v_cndmask_b32_e64 v241, v241, -v241, s[38:39]
	v_cndmask_b32_e64 v243, v243, -v243, s[38:39]
	v_cndmask_b32_e64 v245, v245, -v245, s[38:39]
	v_cndmask_b32_e64 v247, v247, -v247, s[38:39]
	s_waitcnt lgkmcnt(0)
	v_mul_f32_e32 v224, v154, v233
	v_mul_f32_e32 v225, v155, v235
	v_mul_f32_e32 v226, v156, v237
	v_mul_f32_e32 v227, v157, v239
	v_mul_f32_e32 v228, v158, v241
	v_mul_f32_e32 v229, v159, v243
	v_mul_f32_e32 v230, v160, v245
	v_mul_f32_e32 v231, v161, v247
	v_fma_f32 v94, v94, v232, v224
	v_fma_f32 v95, v95, v234, v225
	v_fma_f32 v96, v96, v236, v226
	v_fma_f32 v97, v97, v238, v227
	v_fma_f32 v90, v90, v240, v228
	v_fma_f32 v91, v91, v242, v229
	v_fma_f32 v92, v92, v244, v230
	v_fma_f32 v93, v93, v246, v231
	s_mov_b64 exec, s[0:1]
	ds_bpermute_b32 v154, v167, v86
	ds_bpermute_b32 v155, v167, v87
	ds_bpermute_b32 v156, v167, v88
	ds_bpermute_b32 v157, v167, v89
	ds_bpermute_b32 v158, v167, v82
	ds_bpermute_b32 v159, v167, v83
	ds_bpermute_b32 v160, v167, v84
	ds_bpermute_b32 v161, v167, v85
	s_and_b64 exec, exec, s[14:15]
	s_waitcnt lgkmcnt(0)
	v_mul_f32_e32 v224, v154, v233
	v_mul_f32_e32 v225, v155, v235
	v_mul_f32_e32 v226, v156, v237
	v_mul_f32_e32 v227, v157, v239
	v_mul_f32_e32 v228, v158, v241
	v_mul_f32_e32 v229, v159, v243
	v_mul_f32_e32 v230, v160, v245
	v_mul_f32_e32 v231, v161, v247
	v_fma_f32 v86, v86, v232, v224
	v_fma_f32 v87, v87, v234, v225
	v_fma_f32 v88, v88, v236, v226
	v_fma_f32 v89, v89, v238, v227
	v_fma_f32 v82, v82, v240, v228
	v_fma_f32 v83, v83, v242, v229
	v_fma_f32 v84, v84, v244, v230
	v_fma_f32 v85, v85, v246, v231
.Lfe_q_nr2:
	s_or_b64 exec, exec, s[0:1]
	v_pk_mul_f32 v[94:95], v[94:95], s[28:29] op_sel_hi:[1,0]
	v_pk_mul_f32 v[96:97], v[96:97], s[28:29] op_sel_hi:[1,0]
	v_pk_mul_f32 v[90:91], v[90:91], s[28:29] op_sel_hi:[1,0]
	v_pk_mul_f32 v[92:93], v[92:93], s[28:29] op_sel_hi:[1,0]
	v_cvt_pk_bf16_f32 v130, v94, v95
	v_cvt_pk_bf16_f32 v131, v96, v97
	v_cvt_pk_bf16_f32 v132, v90, v91
	v_cvt_pk_bf16_f32 v133, v92, v93
	global_store_dwordx4 v164, v[130:133], s[34:35] nt
	v_pk_mul_f32 v[86:87], v[86:87], s[28:29] op_sel_hi:[1,0]
	v_pk_mul_f32 v[88:89], v[88:89], s[28:29] op_sel_hi:[1,0]
	v_pk_mul_f32 v[82:83], v[82:83], s[28:29] op_sel_hi:[1,0]
	v_pk_mul_f32 v[84:85], v[84:85], s[28:29] op_sel_hi:[1,0]
	v_cvt_pk_bf16_f32 v134, v86, v87
	v_cvt_pk_bf16_f32 v135, v88, v89
	v_cvt_pk_bf16_f32 v136, v82, v83
	v_cvt_pk_bf16_f32 v137, v84, v85
	global_store_dwordx4 v164, v[134:137], s[34:35] offset:256 nt
	v_add_u32_e32 v166, 0x13e000, v165
	v_pk_mul_f32 v[78:79], v[78:79], v[182:183] op_sel_hi:[1,0]
	v_pk_mul_f32 v[80:81], v[80:81], v[182:183] op_sel_hi:[1,0]
	v_pk_mul_f32 v[74:75], v[74:75], v[182:183] op_sel_hi:[1,0]
	v_pk_mul_f32 v[76:77], v[76:77], v[182:183] op_sel_hi:[1,0]
	v_pk_mul_f32 v[70:71], v[70:71], v[182:183] op_sel_hi:[1,0]
	v_pk_mul_f32 v[72:73], v[72:73], v[182:183] op_sel_hi:[1,0]
	v_pk_mul_f32 v[66:67], v[66:67], v[182:183] op_sel_hi:[1,0]
	v_pk_mul_f32 v[68:69], v[68:69], v[182:183] op_sel_hi:[1,0]
	s_and_saveexec_b64 s[0:1], s[14:15]
	s_cbranch_execz .Lfe_q_nr3
	ds_read_b128 v[232:235], v168 offset:3072
	ds_read_b128 v[236:239], v168 offset:3088
	ds_read_b128 v[240:243], v168 offset:3104
	ds_read_b128 v[244:247], v168 offset:3120
	s_mov_b64 exec, s[0:1]
	ds_bpermute_b32 v154, v167, v78
	ds_bpermute_b32 v155, v167, v79
	ds_bpermute_b32 v156, v167, v80
	ds_bpermute_b32 v157, v167, v81
	ds_bpermute_b32 v158, v167, v74
	ds_bpermute_b32 v159, v167, v75
	ds_bpermute_b32 v160, v167, v76
	ds_bpermute_b32 v161, v167, v77
	s_and_b64 exec, exec, s[14:15]
	s_waitcnt lgkmcnt(8)
	v_cndmask_b32_e64 v233, v233, -v233, s[38:39]
	v_cndmask_b32_e64 v235, v235, -v235, s[38:39]
	v_cndmask_b32_e64 v237, v237, -v237, s[38:39]
	v_cndmask_b32_e64 v239, v239, -v239, s[38:39]
	v_cndmask_b32_e64 v241, v241, -v241, s[38:39]
	v_cndmask_b32_e64 v243, v243, -v243, s[38:39]
	v_cndmask_b32_e64 v245, v245, -v245, s[38:39]
	v_cndmask_b32_e64 v247, v247, -v247, s[38:39]
	s_waitcnt lgkmcnt(0)
	v_mul_f32_e32 v224, v154, v233
	v_mul_f32_e32 v225, v155, v235
	v_mul_f32_e32 v226, v156, v237
	v_mul_f32_e32 v227, v157, v239
	v_mul_f32_e32 v228, v158, v241
	v_mul_f32_e32 v229, v159, v243
	v_mul_f32_e32 v230, v160, v245
	v_mul_f32_e32 v231, v161, v247
	v_fma_f32 v78, v78, v232, v224
	v_fma_f32 v79, v79, v234, v225
	v_fma_f32 v80, v80, v236, v226
	v_fma_f32 v81, v81, v238, v227
	v_fma_f32 v74, v74, v240, v228
	v_fma_f32 v75, v75, v242, v229
	v_fma_f32 v76, v76, v244, v230
	v_fma_f32 v77, v77, v246, v231
	s_mov_b64 exec, s[0:1]
	ds_bpermute_b32 v154, v167, v70
	ds_bpermute_b32 v155, v167, v71
	ds_bpermute_b32 v156, v167, v72
	ds_bpermute_b32 v157, v167, v73
	ds_bpermute_b32 v158, v167, v66
	ds_bpermute_b32 v159, v167, v67
	ds_bpermute_b32 v160, v167, v68
	ds_bpermute_b32 v161, v167, v69
	s_and_b64 exec, exec, s[14:15]
	s_waitcnt lgkmcnt(0)
	v_mul_f32_e32 v224, v154, v233
	v_mul_f32_e32 v225, v155, v235
	v_mul_f32_e32 v226, v156, v237
	v_mul_f32_e32 v227, v157, v239
	v_mul_f32_e32 v228, v158, v241
	v_mul_f32_e32 v229, v159, v243
	v_mul_f32_e32 v230, v160, v245
	v_mul_f32_e32 v231, v161, v247
	v_fma_f32 v70, v70, v232, v224
	v_fma_f32 v71, v71, v234, v225
	v_fma_f32 v72, v72, v236, v226
	v_fma_f32 v73, v73, v238, v227
	v_fma_f32 v66, v66, v240, v228
	v_fma_f32 v67, v67, v242, v229
	v_fma_f32 v68, v68, v244, v230
	v_fma_f32 v69, v69, v246, v231
.Lfe_q_nr3:
	s_or_b64 exec, exec, s[0:1]
	v_pk_mul_f32 v[78:79], v[78:79], s[28:29] op_sel_hi:[1,0]
	v_pk_mul_f32 v[80:81], v[80:81], s[28:29] op_sel_hi:[1,0]
	v_pk_mul_f32 v[74:75], v[74:75], s[28:29] op_sel_hi:[1,0]
	v_pk_mul_f32 v[76:77], v[76:77], s[28:29] op_sel_hi:[1,0]
	v_cvt_pk_bf16_f32 v130, v78, v79
	v_cvt_pk_bf16_f32 v131, v80, v81
	v_cvt_pk_bf16_f32 v132, v74, v75
	v_cvt_pk_bf16_f32 v133, v76, v77
	global_store_dwordx4 v166, v[130:133], s[34:35] nt
	v_pk_mul_f32 v[70:71], v[70:71], s[28:29] op_sel_hi:[1,0]
	v_pk_mul_f32 v[72:73], v[72:73], s[28:29] op_sel_hi:[1,0]
	v_pk_mul_f32 v[66:67], v[66:67], s[28:29] op_sel_hi:[1,0]
	v_pk_mul_f32 v[68:69], v[68:69], s[28:29] op_sel_hi:[1,0]
	v_cvt_pk_bf16_f32 v134, v70, v71
	v_cvt_pk_bf16_f32 v135, v72, v73
	v_cvt_pk_bf16_f32 v136, v66, v67
	v_cvt_pk_bf16_f32 v137, v68, v69
	global_store_dwordx4 v166, v[134:137], s[34:35] offset:256 nt
	v_add_u32_e32 v164, 0x350000, v165
	v_pk_mul_f32 v[62:63], v[62:63], v[184:185] op_sel_hi:[1,0]
	v_pk_mul_f32 v[64:65], v[64:65], v[184:185] op_sel_hi:[1,0]
	v_pk_mul_f32 v[58:59], v[58:59], v[184:185] op_sel_hi:[1,0]
	v_pk_mul_f32 v[60:61], v[60:61], v[184:185] op_sel_hi:[1,0]
	v_pk_mul_f32 v[54:55], v[54:55], v[184:185] op_sel_hi:[1,0]
	v_pk_mul_f32 v[56:57], v[56:57], v[184:185] op_sel_hi:[1,0]
	v_pk_mul_f32 v[50:51], v[50:51], v[184:185] op_sel_hi:[1,0]
	v_pk_mul_f32 v[52:53], v[52:53], v[184:185] op_sel_hi:[1,0]
	s_and_saveexec_b64 s[0:1], s[14:15]
	s_cbranch_execz .Lfe_q_nr4
	ds_read_b128 v[232:235], v168 offset:8192
	ds_read_b128 v[236:239], v168 offset:8208
	ds_read_b128 v[240:243], v168 offset:8224
	ds_read_b128 v[244:247], v168 offset:8240
	s_mov_b64 exec, s[0:1]
	ds_bpermute_b32 v154, v167, v62
	ds_bpermute_b32 v155, v167, v63
	ds_bpermute_b32 v156, v167, v64
	ds_bpermute_b32 v157, v167, v65
	ds_bpermute_b32 v158, v167, v58
	ds_bpermute_b32 v159, v167, v59
	ds_bpermute_b32 v160, v167, v60
	ds_bpermute_b32 v161, v167, v61
	s_and_b64 exec, exec, s[14:15]
	s_waitcnt lgkmcnt(8)
	v_cndmask_b32_e64 v233, v233, -v233, s[38:39]
	v_cndmask_b32_e64 v235, v235, -v235, s[38:39]
	v_cndmask_b32_e64 v237, v237, -v237, s[38:39]
	v_cndmask_b32_e64 v239, v239, -v239, s[38:39]
	v_cndmask_b32_e64 v241, v241, -v241, s[38:39]
	v_cndmask_b32_e64 v243, v243, -v243, s[38:39]
	v_cndmask_b32_e64 v245, v245, -v245, s[38:39]
	v_cndmask_b32_e64 v247, v247, -v247, s[38:39]
	s_waitcnt lgkmcnt(0)
	v_mul_f32_e32 v224, v154, v233
	v_mul_f32_e32 v225, v155, v235
	v_mul_f32_e32 v226, v156, v237
	v_mul_f32_e32 v227, v157, v239
	v_mul_f32_e32 v228, v158, v241
	v_mul_f32_e32 v229, v159, v243
	v_mul_f32_e32 v230, v160, v245
	v_mul_f32_e32 v231, v161, v247
	v_fma_f32 v62, v62, v232, v224
	v_fma_f32 v63, v63, v234, v225
	v_fma_f32 v64, v64, v236, v226
	v_fma_f32 v65, v65, v238, v227
	v_fma_f32 v58, v58, v240, v228
	v_fma_f32 v59, v59, v242, v229
	v_fma_f32 v60, v60, v244, v230
	v_fma_f32 v61, v61, v246, v231
	s_mov_b64 exec, s[0:1]
	ds_bpermute_b32 v154, v167, v54
	ds_bpermute_b32 v155, v167, v55
	ds_bpermute_b32 v156, v167, v56
	ds_bpermute_b32 v157, v167, v57
	ds_bpermute_b32 v158, v167, v50
	ds_bpermute_b32 v159, v167, v51
	ds_bpermute_b32 v160, v167, v52
	ds_bpermute_b32 v161, v167, v53
	s_and_b64 exec, exec, s[14:15]
	s_waitcnt lgkmcnt(0)
	v_mul_f32_e32 v224, v154, v233
	v_mul_f32_e32 v225, v155, v235
	v_mul_f32_e32 v226, v156, v237
	v_mul_f32_e32 v227, v157, v239
	v_mul_f32_e32 v228, v158, v241
	v_mul_f32_e32 v229, v159, v243
	v_mul_f32_e32 v230, v160, v245
	v_mul_f32_e32 v231, v161, v247
	v_fma_f32 v54, v54, v232, v224
	v_fma_f32 v55, v55, v234, v225
	v_fma_f32 v56, v56, v236, v226
	v_fma_f32 v57, v57, v238, v227
	v_fma_f32 v50, v50, v240, v228
	v_fma_f32 v51, v51, v242, v229
	v_fma_f32 v52, v52, v244, v230
	v_fma_f32 v53, v53, v246, v231
.Lfe_q_nr4:
	s_or_b64 exec, exec, s[0:1]
	v_pk_mul_f32 v[62:63], v[62:63], s[28:29] op_sel_hi:[1,0]
	v_pk_mul_f32 v[64:65], v[64:65], s[28:29] op_sel_hi:[1,0]
	v_pk_mul_f32 v[58:59], v[58:59], s[28:29] op_sel_hi:[1,0]
	v_pk_mul_f32 v[60:61], v[60:61], s[28:29] op_sel_hi:[1,0]
	v_cvt_pk_bf16_f32 v130, v62, v63
	v_cvt_pk_bf16_f32 v131, v64, v65
	v_cvt_pk_bf16_f32 v132, v58, v59
	v_cvt_pk_bf16_f32 v133, v60, v61
	global_store_dwordx4 v164, v[130:133], s[34:35] nt
	v_pk_mul_f32 v[54:55], v[54:55], s[28:29] op_sel_hi:[1,0]
	v_pk_mul_f32 v[56:57], v[56:57], s[28:29] op_sel_hi:[1,0]
	v_pk_mul_f32 v[50:51], v[50:51], s[28:29] op_sel_hi:[1,0]
	v_pk_mul_f32 v[52:53], v[52:53], s[28:29] op_sel_hi:[1,0]
	v_cvt_pk_bf16_f32 v134, v54, v55
	v_cvt_pk_bf16_f32 v135, v56, v57
	v_cvt_pk_bf16_f32 v136, v50, v51
	v_cvt_pk_bf16_f32 v137, v52, v53
	global_store_dwordx4 v164, v[134:137], s[34:35] offset:256 nt
	v_add_u32_e32 v166, 0x3ba000, v165
	v_pk_mul_f32 v[46:47], v[46:47], v[186:187] op_sel_hi:[1,0]
	v_pk_mul_f32 v[48:49], v[48:49], v[186:187] op_sel_hi:[1,0]
	v_pk_mul_f32 v[42:43], v[42:43], v[186:187] op_sel_hi:[1,0]
	v_pk_mul_f32 v[44:45], v[44:45], v[186:187] op_sel_hi:[1,0]
	v_pk_mul_f32 v[38:39], v[38:39], v[186:187] op_sel_hi:[1,0]
	v_pk_mul_f32 v[40:41], v[40:41], v[186:187] op_sel_hi:[1,0]
	v_pk_mul_f32 v[34:35], v[34:35], v[186:187] op_sel_hi:[1,0]
	v_pk_mul_f32 v[36:37], v[36:37], v[186:187] op_sel_hi:[1,0]
	s_and_saveexec_b64 s[0:1], s[14:15]
	s_cbranch_execz .Lfe_q_nr5
	ds_read_b128 v[232:235], v168 offset:9216
	ds_read_b128 v[236:239], v168 offset:9232
	ds_read_b128 v[240:243], v168 offset:9248
	ds_read_b128 v[244:247], v168 offset:9264
	s_mov_b64 exec, s[0:1]
	ds_bpermute_b32 v154, v167, v46
	ds_bpermute_b32 v155, v167, v47
	ds_bpermute_b32 v156, v167, v48
	ds_bpermute_b32 v157, v167, v49
	ds_bpermute_b32 v158, v167, v42
	ds_bpermute_b32 v159, v167, v43
	ds_bpermute_b32 v160, v167, v44
	ds_bpermute_b32 v161, v167, v45
	s_and_b64 exec, exec, s[14:15]
	s_waitcnt lgkmcnt(8)
	v_cndmask_b32_e64 v233, v233, -v233, s[38:39]
	v_cndmask_b32_e64 v235, v235, -v235, s[38:39]
	v_cndmask_b32_e64 v237, v237, -v237, s[38:39]
	v_cndmask_b32_e64 v239, v239, -v239, s[38:39]
	v_cndmask_b32_e64 v241, v241, -v241, s[38:39]
	v_cndmask_b32_e64 v243, v243, -v243, s[38:39]
	v_cndmask_b32_e64 v245, v245, -v245, s[38:39]
	v_cndmask_b32_e64 v247, v247, -v247, s[38:39]
	s_waitcnt lgkmcnt(0)
	v_mul_f32_e32 v224, v154, v233
	v_mul_f32_e32 v225, v155, v235
	v_mul_f32_e32 v226, v156, v237
	v_mul_f32_e32 v227, v157, v239
	v_mul_f32_e32 v228, v158, v241
	v_mul_f32_e32 v229, v159, v243
	v_mul_f32_e32 v230, v160, v245
	v_mul_f32_e32 v231, v161, v247
	v_fma_f32 v46, v46, v232, v224
	v_fma_f32 v47, v47, v234, v225
	v_fma_f32 v48, v48, v236, v226
	v_fma_f32 v49, v49, v238, v227
	v_fma_f32 v42, v42, v240, v228
	v_fma_f32 v43, v43, v242, v229
	v_fma_f32 v44, v44, v244, v230
	v_fma_f32 v45, v45, v246, v231
	s_mov_b64 exec, s[0:1]
	ds_bpermute_b32 v154, v167, v38
	ds_bpermute_b32 v155, v167, v39
	ds_bpermute_b32 v156, v167, v40
	ds_bpermute_b32 v157, v167, v41
	ds_bpermute_b32 v158, v167, v34
	ds_bpermute_b32 v159, v167, v35
	ds_bpermute_b32 v160, v167, v36
	ds_bpermute_b32 v161, v167, v37
	s_and_b64 exec, exec, s[14:15]
	s_waitcnt lgkmcnt(0)
	v_mul_f32_e32 v224, v154, v233
	v_mul_f32_e32 v225, v155, v235
	v_mul_f32_e32 v226, v156, v237
	v_mul_f32_e32 v227, v157, v239
	v_mul_f32_e32 v228, v158, v241
	v_mul_f32_e32 v229, v159, v243
	v_mul_f32_e32 v230, v160, v245
	v_mul_f32_e32 v231, v161, v247
	v_fma_f32 v38, v38, v232, v224
	v_fma_f32 v39, v39, v234, v225
	v_fma_f32 v40, v40, v236, v226
	v_fma_f32 v41, v41, v238, v227
	v_fma_f32 v34, v34, v240, v228
	v_fma_f32 v35, v35, v242, v229
	v_fma_f32 v36, v36, v244, v230
	v_fma_f32 v37, v37, v246, v231
.Lfe_q_nr5:
	s_or_b64 exec, exec, s[0:1]
	v_pk_mul_f32 v[46:47], v[46:47], s[28:29] op_sel_hi:[1,0]
	v_pk_mul_f32 v[48:49], v[48:49], s[28:29] op_sel_hi:[1,0]
	v_pk_mul_f32 v[42:43], v[42:43], s[28:29] op_sel_hi:[1,0]
	v_pk_mul_f32 v[44:45], v[44:45], s[28:29] op_sel_hi:[1,0]
	v_cvt_pk_bf16_f32 v130, v46, v47
	v_cvt_pk_bf16_f32 v131, v48, v49
	v_cvt_pk_bf16_f32 v132, v42, v43
	v_cvt_pk_bf16_f32 v133, v44, v45
	global_store_dwordx4 v166, v[130:133], s[34:35] nt
	v_pk_mul_f32 v[38:39], v[38:39], s[28:29] op_sel_hi:[1,0]
	v_pk_mul_f32 v[40:41], v[40:41], s[28:29] op_sel_hi:[1,0]
	v_pk_mul_f32 v[34:35], v[34:35], s[28:29] op_sel_hi:[1,0]
	v_pk_mul_f32 v[36:37], v[36:37], s[28:29] op_sel_hi:[1,0]
	v_cvt_pk_bf16_f32 v134, v38, v39
	v_cvt_pk_bf16_f32 v135, v40, v41
	v_cvt_pk_bf16_f32 v136, v34, v35
	v_cvt_pk_bf16_f32 v137, v36, v37
	global_store_dwordx4 v166, v[134:137], s[34:35] offset:256 nt
	v_add_u32_e32 v164, 0x424000, v165
	v_pk_mul_f32 v[30:31], v[30:31], v[188:189] op_sel_hi:[1,0]
	v_pk_mul_f32 v[32:33], v[32:33], v[188:189] op_sel_hi:[1,0]
	v_pk_mul_f32 v[26:27], v[26:27], v[188:189] op_sel_hi:[1,0]
	v_pk_mul_f32 v[28:29], v[28:29], v[188:189] op_sel_hi:[1,0]
	v_pk_mul_f32 v[22:23], v[22:23], v[188:189] op_sel_hi:[1,0]
	v_pk_mul_f32 v[24:25], v[24:25], v[188:189] op_sel_hi:[1,0]
	v_pk_mul_f32 v[18:19], v[18:19], v[188:189] op_sel_hi:[1,0]
	v_pk_mul_f32 v[20:21], v[20:21], v[188:189] op_sel_hi:[1,0]
	s_and_saveexec_b64 s[0:1], s[14:15]
	s_cbranch_execz .Lfe_q_nr6
	ds_read_b128 v[232:235], v168 offset:10240
	ds_read_b128 v[236:239], v168 offset:10256
	ds_read_b128 v[240:243], v168 offset:10272
	ds_read_b128 v[244:247], v168 offset:10288
	s_mov_b64 exec, s[0:1]
	ds_bpermute_b32 v154, v167, v30
	ds_bpermute_b32 v155, v167, v31
	ds_bpermute_b32 v156, v167, v32
	ds_bpermute_b32 v157, v167, v33
	ds_bpermute_b32 v158, v167, v26
	ds_bpermute_b32 v159, v167, v27
	ds_bpermute_b32 v160, v167, v28
	ds_bpermute_b32 v161, v167, v29
	s_and_b64 exec, exec, s[14:15]
	s_waitcnt lgkmcnt(8)
	v_cndmask_b32_e64 v233, v233, -v233, s[38:39]
	v_cndmask_b32_e64 v235, v235, -v235, s[38:39]
	v_cndmask_b32_e64 v237, v237, -v237, s[38:39]
	v_cndmask_b32_e64 v239, v239, -v239, s[38:39]
	v_cndmask_b32_e64 v241, v241, -v241, s[38:39]
	v_cndmask_b32_e64 v243, v243, -v243, s[38:39]
	v_cndmask_b32_e64 v245, v245, -v245, s[38:39]
	v_cndmask_b32_e64 v247, v247, -v247, s[38:39]
	s_waitcnt lgkmcnt(0)
	v_mul_f32_e32 v224, v154, v233
	v_mul_f32_e32 v225, v155, v235
	v_mul_f32_e32 v226, v156, v237
	v_mul_f32_e32 v227, v157, v239
	v_mul_f32_e32 v228, v158, v241
	v_mul_f32_e32 v229, v159, v243
	v_mul_f32_e32 v230, v160, v245
	v_mul_f32_e32 v231, v161, v247
	v_fma_f32 v30, v30, v232, v224
	v_fma_f32 v31, v31, v234, v225
	v_fma_f32 v32, v32, v236, v226
	v_fma_f32 v33, v33, v238, v227
	v_fma_f32 v26, v26, v240, v228
	v_fma_f32 v27, v27, v242, v229
	v_fma_f32 v28, v28, v244, v230
	v_fma_f32 v29, v29, v246, v231
	s_mov_b64 exec, s[0:1]
	ds_bpermute_b32 v154, v167, v22
	ds_bpermute_b32 v155, v167, v23
	ds_bpermute_b32 v156, v167, v24
	ds_bpermute_b32 v157, v167, v25
	ds_bpermute_b32 v158, v167, v18
	ds_bpermute_b32 v159, v167, v19
	ds_bpermute_b32 v160, v167, v20
	ds_bpermute_b32 v161, v167, v21
	s_and_b64 exec, exec, s[14:15]
	s_waitcnt lgkmcnt(0)
	v_mul_f32_e32 v224, v154, v233
	v_mul_f32_e32 v225, v155, v235
	v_mul_f32_e32 v226, v156, v237
	v_mul_f32_e32 v227, v157, v239
	v_mul_f32_e32 v228, v158, v241
	v_mul_f32_e32 v229, v159, v243
	v_mul_f32_e32 v230, v160, v245
	v_mul_f32_e32 v231, v161, v247
	v_fma_f32 v22, v22, v232, v224
	v_fma_f32 v23, v23, v234, v225
	v_fma_f32 v24, v24, v236, v226
	v_fma_f32 v25, v25, v238, v227
	v_fma_f32 v18, v18, v240, v228
	v_fma_f32 v19, v19, v242, v229
	v_fma_f32 v20, v20, v244, v230
	v_fma_f32 v21, v21, v246, v231
.Lfe_q_nr6:
	s_or_b64 exec, exec, s[0:1]
	v_pk_mul_f32 v[30:31], v[30:31], s[28:29] op_sel_hi:[1,0]
	v_pk_mul_f32 v[32:33], v[32:33], s[28:29] op_sel_hi:[1,0]
	v_pk_mul_f32 v[26:27], v[26:27], s[28:29] op_sel_hi:[1,0]
	v_pk_mul_f32 v[28:29], v[28:29], s[28:29] op_sel_hi:[1,0]
	v_cvt_pk_bf16_f32 v130, v30, v31
	v_cvt_pk_bf16_f32 v131, v32, v33
	v_cvt_pk_bf16_f32 v132, v26, v27
	v_cvt_pk_bf16_f32 v133, v28, v29
	global_store_dwordx4 v164, v[130:133], s[34:35] nt
	v_pk_mul_f32 v[22:23], v[22:23], s[28:29] op_sel_hi:[1,0]
	v_pk_mul_f32 v[24:25], v[24:25], s[28:29] op_sel_hi:[1,0]
	v_pk_mul_f32 v[18:19], v[18:19], s[28:29] op_sel_hi:[1,0]
	v_pk_mul_f32 v[20:21], v[20:21], s[28:29] op_sel_hi:[1,0]
	v_cvt_pk_bf16_f32 v134, v22, v23
	v_cvt_pk_bf16_f32 v135, v24, v25
	v_cvt_pk_bf16_f32 v136, v18, v19
	v_cvt_pk_bf16_f32 v137, v20, v21
	global_store_dwordx4 v164, v[134:137], s[34:35] offset:256 nt
	v_add_u32_e32 v166, 0x48e000, v165
	v_pk_mul_f32 v[14:15], v[14:15], v[190:191] op_sel_hi:[1,0]
	v_pk_mul_f32 v[16:17], v[16:17], v[190:191] op_sel_hi:[1,0]
	v_pk_mul_f32 v[10:11], v[10:11], v[190:191] op_sel_hi:[1,0]
	v_pk_mul_f32 v[12:13], v[12:13], v[190:191] op_sel_hi:[1,0]
	v_pk_mul_f32 v[6:7], v[6:7], v[190:191] op_sel_hi:[1,0]
	v_pk_mul_f32 v[8:9], v[8:9], v[190:191] op_sel_hi:[1,0]
	v_pk_mul_f32 v[2:3], v[2:3], v[190:191] op_sel_hi:[1,0]
	v_pk_mul_f32 v[4:5], v[4:5], v[190:191] op_sel_hi:[1,0]
	s_and_saveexec_b64 s[0:1], s[14:15]
	s_cbranch_execz .Lfe_q_nr7
	ds_read_b128 v[232:235], v168 offset:11264
	ds_read_b128 v[236:239], v168 offset:11280
	ds_read_b128 v[240:243], v168 offset:11296
	ds_read_b128 v[244:247], v168 offset:11312
	s_mov_b64 exec, s[0:1]
	ds_bpermute_b32 v154, v167, v14
	ds_bpermute_b32 v155, v167, v15
	ds_bpermute_b32 v156, v167, v16
	ds_bpermute_b32 v157, v167, v17
	ds_bpermute_b32 v158, v167, v10
	ds_bpermute_b32 v159, v167, v11
	ds_bpermute_b32 v160, v167, v12
	ds_bpermute_b32 v161, v167, v13
	s_and_b64 exec, exec, s[14:15]
	s_waitcnt lgkmcnt(8)
	v_cndmask_b32_e64 v233, v233, -v233, s[38:39]
	v_cndmask_b32_e64 v235, v235, -v235, s[38:39]
	v_cndmask_b32_e64 v237, v237, -v237, s[38:39]
	v_cndmask_b32_e64 v239, v239, -v239, s[38:39]
	v_cndmask_b32_e64 v241, v241, -v241, s[38:39]
	v_cndmask_b32_e64 v243, v243, -v243, s[38:39]
	v_cndmask_b32_e64 v245, v245, -v245, s[38:39]
	v_cndmask_b32_e64 v247, v247, -v247, s[38:39]
	s_waitcnt lgkmcnt(0)
	v_mul_f32_e32 v224, v154, v233
	v_mul_f32_e32 v225, v155, v235
	v_mul_f32_e32 v226, v156, v237
	v_mul_f32_e32 v227, v157, v239
	v_mul_f32_e32 v228, v158, v241
	v_mul_f32_e32 v229, v159, v243
	v_mul_f32_e32 v230, v160, v245
	v_mul_f32_e32 v231, v161, v247
	v_fma_f32 v14, v14, v232, v224
	v_fma_f32 v15, v15, v234, v225
	v_fma_f32 v16, v16, v236, v226
	v_fma_f32 v17, v17, v238, v227
	v_fma_f32 v10, v10, v240, v228
	v_fma_f32 v11, v11, v242, v229
	v_fma_f32 v12, v12, v244, v230
	v_fma_f32 v13, v13, v246, v231
	s_mov_b64 exec, s[0:1]
	ds_bpermute_b32 v154, v167, v6
	ds_bpermute_b32 v155, v167, v7
	ds_bpermute_b32 v156, v167, v8
	ds_bpermute_b32 v157, v167, v9
	ds_bpermute_b32 v158, v167, v2
	ds_bpermute_b32 v159, v167, v3
	ds_bpermute_b32 v160, v167, v4
	ds_bpermute_b32 v161, v167, v5
	s_and_b64 exec, exec, s[14:15]
	s_waitcnt lgkmcnt(0)
	v_mul_f32_e32 v224, v154, v233
	v_mul_f32_e32 v225, v155, v235
	v_mul_f32_e32 v226, v156, v237
	v_mul_f32_e32 v227, v157, v239
	v_mul_f32_e32 v228, v158, v241
	v_mul_f32_e32 v229, v159, v243
	v_mul_f32_e32 v230, v160, v245
	v_mul_f32_e32 v231, v161, v247
	v_fma_f32 v6, v6, v232, v224
	v_fma_f32 v7, v7, v234, v225
	v_fma_f32 v8, v8, v236, v226
	v_fma_f32 v9, v9, v238, v227
	v_fma_f32 v2, v2, v240, v228
	v_fma_f32 v3, v3, v242, v229
	v_fma_f32 v4, v4, v244, v230
	v_fma_f32 v5, v5, v246, v231
.Lfe_q_nr7:
	s_or_b64 exec, exec, s[0:1]
	v_pk_mul_f32 v[14:15], v[14:15], s[28:29] op_sel_hi:[1,0]
	v_pk_mul_f32 v[16:17], v[16:17], s[28:29] op_sel_hi:[1,0]
	v_pk_mul_f32 v[10:11], v[10:11], s[28:29] op_sel_hi:[1,0]
	v_pk_mul_f32 v[12:13], v[12:13], s[28:29] op_sel_hi:[1,0]
	v_cvt_pk_bf16_f32 v130, v14, v15
	v_cvt_pk_bf16_f32 v131, v16, v17
	v_cvt_pk_bf16_f32 v132, v10, v11
	v_cvt_pk_bf16_f32 v133, v12, v13
	global_store_dwordx4 v166, v[130:133], s[34:35] nt
	v_pk_mul_f32 v[6:7], v[6:7], s[28:29] op_sel_hi:[1,0]
	v_pk_mul_f32 v[8:9], v[8:9], s[28:29] op_sel_hi:[1,0]
	v_pk_mul_f32 v[2:3], v[2:3], s[28:29] op_sel_hi:[1,0]
	v_pk_mul_f32 v[4:5], v[4:5], s[28:29] op_sel_hi:[1,0]
	v_cvt_pk_bf16_f32 v134, v6, v7
	v_cvt_pk_bf16_f32 v135, v8, v9
	v_cvt_pk_bf16_f32 v136, v2, v3
	v_cvt_pk_bf16_f32 v137, v4, v5
	global_store_dwordx4 v166, v[134:137], s[34:35] offset:256 nt
	s_branch .Lfe_done
.Lfe_vb:
	s_lshl_b32 s19, s42, 8
	s_add_i32 s19, s19, s71
	v_or_b32_e32 v162, s19, v147
	ds_read_b32 v176, v172
	ds_read_b32 v178, v172 offset:64
	ds_read_b32 v180, v172 offset:128
	ds_read_b32 v182, v172 offset:192
	ds_read_b32 v184, v172 offset:512
	ds_read_b32 v186, v172 offset:576
	ds_read_b32 v188, v172 offset:640
	ds_read_b32 v190, v172 offset:704
	v_and_b32_e32 v167, 24, v174
	v_lshlrev_b32_e32 v167, 5, v167
	v_lshl_add_u32 v167, v147, 1, v167
	s_add_i32 s27, s67, 0xc000
	v_add_u32_e32 v167, s27, v167
	v_and_b32_e32 v168, 31, v217
	v_lshlrev_b32_e32 v168, 5, v168
	v_lshrrev_b32_e32 v169, 5, v217
	v_lshl_add_u32 v168, v169, 13, v168
	v_add_u32_e32 v168, s27, v168
	v_and_b32_e32 v165, 0x60, v174
	v_and_b32_e32 v164, 31, v217
	v_or_b32_e32 v165, v165, v164
	v_lshl_or_b32 v165, v169, 7, v165
	s_sub_i32 s27, s35, 12
	s_lshl_b32 s27, s27, 8
	v_add_u32_e32 v165, s27, v165
	s_lshl_b32 s27, s42, 11
	v_add_u32_e32 v165, s27, v165
	v_lshlrev_b32_e32 v165, 8, v165
	s_lshl_b32 s27, s71, 1
	v_add_u32_e32 v165, s27, v165
	v_lshlrev_b32_e32 v163, 3, v162
	v_readlane_b32 s44, v251, 16
	v_readlane_b32 s45, v251, 17
	s_mov_b32 s0, 1.0
	s_mov_b32 s28, 0xbfb8aa3b
	s_mov_b32 s2, 0x3d372713
	s_mov_b32 s48, 0x3fcc422a
	v_mov_b32_e32 v192, 0
	v_mov_b32_e32 v193, 0
	v_mov_b32_e32 v194, 0
	v_mov_b32_e32 v195, 0
	v_mov_b32_e32 v196, 0
	v_mov_b32_e32 v197, 0
	v_mov_b32_e32 v198, 0
	v_mov_b32_e32 v199, 0
	v_mov_b32_e32 v224, 0
	v_mov_b32_e32 v225, 0
	v_mov_b32_e32 v226, 0
	v_mov_b32_e32 v227, 0
	v_mov_b32_e32 v228, 0
	v_mov_b32_e32 v229, 0
	v_mov_b32_e32 v230, 0
	v_mov_b32_e32 v231, 0
	s_waitcnt lgkmcnt(0)
	v_pk_mul_f32 v[126:127], v[126:127], v[176:177] op_sel_hi:[1,0]
	v_pk_mul_f32 v[128:129], v[128:129], v[176:177] op_sel_hi:[1,0]
	v_pk_mul_f32 v[122:123], v[122:123], v[176:177] op_sel_hi:[1,0]
	v_pk_mul_f32 v[124:125], v[124:125], v[176:177] op_sel_hi:[1,0]
	v_pk_mul_f32 v[154:155], v[126:127], s[2:3] op_sel_hi:[1,0]
	v_pk_mul_f32 v[156:157], v[128:129], s[2:3] op_sel_hi:[1,0]
	v_pk_mul_f32 v[158:159], v[122:123], s[2:3] op_sel_hi:[1,0]
	v_pk_mul_f32 v[160:161], v[124:125], s[2:3] op_sel_hi:[1,0]
	v_pk_mul_f32 v[154:155], v[126:127], v[154:155]
	v_pk_mul_f32 v[156:157], v[128:129], v[156:157]
	v_pk_mul_f32 v[158:159], v[122:123], v[158:159]
	v_pk_mul_f32 v[160:161], v[124:125], v[160:161]
	v_pk_fma_f32 v[154:155], v[126:127], v[154:155], v[126:127]
	v_pk_fma_f32 v[156:157], v[128:129], v[156:157], v[128:129]
	v_pk_fma_f32 v[158:159], v[122:123], v[158:159], v[122:123]
	v_pk_fma_f32 v[160:161], v[124:125], v[160:161], v[124:125]
	v_pk_mul_f32 v[154:155], v[154:155], s[48:49] op_sel_hi:[1,0]
	v_pk_mul_f32 v[156:157], v[156:157], s[48:49] op_sel_hi:[1,0]
	v_pk_mul_f32 v[158:159], v[158:159], s[48:49] op_sel_hi:[1,0]
	v_pk_mul_f32 v[160:161], v[160:161], s[48:49] op_sel_hi:[1,0]
	v_pk_mul_f32 v[154:155], v[154:155], s[28:29] op_sel_hi:[1,0]
	v_pk_mul_f32 v[156:157], v[156:157], s[28:29] op_sel_hi:[1,0]
	v_pk_mul_f32 v[158:159], v[158:159], s[28:29] op_sel_hi:[1,0]
	v_pk_mul_f32 v[160:161], v[160:161], s[28:29] op_sel_hi:[1,0]
	v_exp_f32_e32 v154, v154
	v_exp_f32_e32 v155, v155
	v_exp_f32_e32 v156, v156
	v_exp_f32_e32 v157, v157
	v_exp_f32_e32 v158, v158
	v_exp_f32_e32 v159, v159
	v_exp_f32_e32 v160, v160
	v_exp_f32_e32 v161, v161
	v_pk_add_f32 v[154:155], v[154:155], s[0:1] op_sel_hi:[1,0]
	v_pk_add_f32 v[156:157], v[156:157], s[0:1] op_sel_hi:[1,0]
	v_pk_add_f32 v[158:159], v[158:159], s[0:1] op_sel_hi:[1,0]
	v_pk_add_f32 v[160:161], v[160:161], s[0:1] op_sel_hi:[1,0]
	v_rcp_f32_e32 v154, v154
	v_rcp_f32_e32 v155, v155
	v_rcp_f32_e32 v156, v156
	v_rcp_f32_e32 v157, v157
	v_rcp_f32_e32 v158, v158
	v_rcp_f32_e32 v159, v159
	v_rcp_f32_e32 v160, v160
	v_rcp_f32_e32 v161, v161
	v_pk_mul_f32 v[126:127], v[126:127], v[154:155]
	v_pk_mul_f32 v[128:129], v[128:129], v[156:157]
	v_pk_mul_f32 v[122:123], v[122:123], v[158:159]
	v_pk_mul_f32 v[124:125], v[124:125], v[160:161]
	v_add_f32_e32 v192, v192, v126
	v_add_f32_e32 v192, v192, v127
	v_add_f32_e32 v192, v192, v128
	v_add_f32_e32 v192, v192, v129
	v_add_f32_e32 v192, v192, v122
	v_add_f32_e32 v192, v192, v123
	v_add_f32_e32 v192, v192, v124
	v_add_f32_e32 v192, v192, v125
	v_fmac_f32_e32 v224, v126, v126
	v_fmac_f32_e32 v224, v127, v127
	v_fmac_f32_e32 v224, v128, v128
	v_fmac_f32_e32 v224, v129, v129
	v_fmac_f32_e32 v224, v122, v122
	v_fmac_f32_e32 v224, v123, v123
	v_fmac_f32_e32 v224, v124, v124
	v_fmac_f32_e32 v224, v125, v125
	v_cvt_pk_bf16_f32 v130, v126, v127
	v_cvt_pk_bf16_f32 v131, v128, v129
	v_cvt_pk_bf16_f32 v132, v122, v123
	v_cvt_pk_bf16_f32 v133, v124, v125
	ds_write_b16 v167, v130 offset:0
	ds_write_b16_d16_hi v167, v130 offset:32
	ds_write_b16 v167, v131 offset:64
	ds_write_b16_d16_hi v167, v131 offset:96
	ds_write_b16 v167, v132 offset:128
	ds_write_b16_d16_hi v167, v132 offset:160
	ds_write_b16 v167, v133 offset:192
	ds_write_b16_d16_hi v167, v133 offset:224
	v_pk_mul_f32 v[118:119], v[118:119], v[176:177] op_sel_hi:[1,0]
	v_pk_mul_f32 v[120:121], v[120:121], v[176:177] op_sel_hi:[1,0]
	v_pk_mul_f32 v[114:115], v[114:115], v[176:177] op_sel_hi:[1,0]
	v_pk_mul_f32 v[116:117], v[116:117], v[176:177] op_sel_hi:[1,0]
	v_pk_mul_f32 v[154:155], v[118:119], s[2:3] op_sel_hi:[1,0]
	v_pk_mul_f32 v[156:157], v[120:121], s[2:3] op_sel_hi:[1,0]
	v_pk_mul_f32 v[158:159], v[114:115], s[2:3] op_sel_hi:[1,0]
	v_pk_mul_f32 v[160:161], v[116:117], s[2:3] op_sel_hi:[1,0]
	v_pk_mul_f32 v[154:155], v[118:119], v[154:155]
	v_pk_mul_f32 v[156:157], v[120:121], v[156:157]
	v_pk_mul_f32 v[158:159], v[114:115], v[158:159]
	v_pk_mul_f32 v[160:161], v[116:117], v[160:161]
	v_pk_fma_f32 v[154:155], v[118:119], v[154:155], v[118:119]
	v_pk_fma_f32 v[156:157], v[120:121], v[156:157], v[120:121]
	v_pk_fma_f32 v[158:159], v[114:115], v[158:159], v[114:115]
	v_pk_fma_f32 v[160:161], v[116:117], v[160:161], v[116:117]
	v_pk_mul_f32 v[154:155], v[154:155], s[48:49] op_sel_hi:[1,0]
	v_pk_mul_f32 v[156:157], v[156:157], s[48:49] op_sel_hi:[1,0]
	v_pk_mul_f32 v[158:159], v[158:159], s[48:49] op_sel_hi:[1,0]
	v_pk_mul_f32 v[160:161], v[160:161], s[48:49] op_sel_hi:[1,0]
	v_pk_mul_f32 v[154:155], v[154:155], s[28:29] op_sel_hi:[1,0]
	v_pk_mul_f32 v[156:157], v[156:157], s[28:29] op_sel_hi:[1,0]
	v_pk_mul_f32 v[158:159], v[158:159], s[28:29] op_sel_hi:[1,0]
	v_pk_mul_f32 v[160:161], v[160:161], s[28:29] op_sel_hi:[1,0]
	v_exp_f32_e32 v154, v154
	v_exp_f32_e32 v155, v155
	v_exp_f32_e32 v156, v156
	v_exp_f32_e32 v157, v157
	v_exp_f32_e32 v158, v158
	v_exp_f32_e32 v159, v159
	v_exp_f32_e32 v160, v160
	v_exp_f32_e32 v161, v161
	v_pk_add_f32 v[154:155], v[154:155], s[0:1] op_sel_hi:[1,0]
	v_pk_add_f32 v[156:157], v[156:157], s[0:1] op_sel_hi:[1,0]
	v_pk_add_f32 v[158:159], v[158:159], s[0:1] op_sel_hi:[1,0]
	v_pk_add_f32 v[160:161], v[160:161], s[0:1] op_sel_hi:[1,0]
	v_rcp_f32_e32 v154, v154
	v_rcp_f32_e32 v155, v155
	v_rcp_f32_e32 v156, v156
	v_rcp_f32_e32 v157, v157
	v_rcp_f32_e32 v158, v158
	v_rcp_f32_e32 v159, v159
	v_rcp_f32_e32 v160, v160
	v_rcp_f32_e32 v161, v161
	v_pk_mul_f32 v[118:119], v[118:119], v[154:155]
	v_pk_mul_f32 v[120:121], v[120:121], v[156:157]
	v_pk_mul_f32 v[114:115], v[114:115], v[158:159]
	v_pk_mul_f32 v[116:117], v[116:117], v[160:161]
	v_add_f32_e32 v192, v192, v118
	v_add_f32_e32 v192, v192, v119
	v_add_f32_e32 v192, v192, v120
	v_add_f32_e32 v192, v192, v121
	v_add_f32_e32 v192, v192, v114
	v_add_f32_e32 v192, v192, v115
	v_add_f32_e32 v192, v192, v116
	v_add_f32_e32 v192, v192, v117
	v_fmac_f32_e32 v224, v118, v118
	v_fmac_f32_e32 v224, v119, v119
	v_fmac_f32_e32 v224, v120, v120
	v_fmac_f32_e32 v224, v121, v121
	v_fmac_f32_e32 v224, v114, v114
	v_fmac_f32_e32 v224, v115, v115
	v_fmac_f32_e32 v224, v116, v116
	v_fmac_f32_e32 v224, v117, v117
	v_cvt_pk_bf16_f32 v130, v118, v119
	v_cvt_pk_bf16_f32 v131, v120, v121
	v_cvt_pk_bf16_f32 v132, v114, v115
	v_cvt_pk_bf16_f32 v133, v116, v117
	ds_write_b16 v167, v130 offset:8192
	ds_write_b16_d16_hi v167, v130 offset:8224
	ds_write_b16 v167, v131 offset:8256
	ds_write_b16_d16_hi v167, v131 offset:8288
	ds_write_b16 v167, v132 offset:8320
	ds_write_b16_d16_hi v167, v132 offset:8352
	ds_write_b16 v167, v133 offset:8384
	ds_write_b16_d16_hi v167, v133 offset:8416
	s_waitcnt lgkmcnt(0)
	ds_read_b128 v[232:235], v168
	ds_read_b128 v[236:239], v168 offset:16
	s_waitcnt lgkmcnt(0)
	global_store_dwordx4 v165, v[232:235], s[44:45]
	global_store_dwordx4 v165, v[236:239], s[44:45] offset:16
	v_pk_mul_f32 v[110:111], v[110:111], v[178:179] op_sel_hi:[1,0]
	v_pk_mul_f32 v[112:113], v[112:113], v[178:179] op_sel_hi:[1,0]
	v_pk_mul_f32 v[106:107], v[106:107], v[178:179] op_sel_hi:[1,0]
	v_pk_mul_f32 v[108:109], v[108:109], v[178:179] op_sel_hi:[1,0]
	v_pk_mul_f32 v[154:155], v[110:111], s[2:3] op_sel_hi:[1,0]
	v_pk_mul_f32 v[156:157], v[112:113], s[2:3] op_sel_hi:[1,0]
	v_pk_mul_f32 v[158:159], v[106:107], s[2:3] op_sel_hi:[1,0]
	v_pk_mul_f32 v[160:161], v[108:109], s[2:3] op_sel_hi:[1,0]
	v_pk_mul_f32 v[154:155], v[110:111], v[154:155]
	v_pk_mul_f32 v[156:157], v[112:113], v[156:157]
	v_pk_mul_f32 v[158:159], v[106:107], v[158:159]
	v_pk_mul_f32 v[160:161], v[108:109], v[160:161]
	v_pk_fma_f32 v[154:155], v[110:111], v[154:155], v[110:111]
	v_pk_fma_f32 v[156:157], v[112:113], v[156:157], v[112:113]
	v_pk_fma_f32 v[158:159], v[106:107], v[158:159], v[106:107]
	v_pk_fma_f32 v[160:161], v[108:109], v[160:161], v[108:109]
	v_pk_mul_f32 v[154:155], v[154:155], s[48:49] op_sel_hi:[1,0]
	v_pk_mul_f32 v[156:157], v[156:157], s[48:49] op_sel_hi:[1,0]
	v_pk_mul_f32 v[158:159], v[158:159], s[48:49] op_sel_hi:[1,0]
	v_pk_mul_f32 v[160:161], v[160:161], s[48:49] op_sel_hi:[1,0]
	v_pk_mul_f32 v[154:155], v[154:155], s[28:29] op_sel_hi:[1,0]
	v_pk_mul_f32 v[156:157], v[156:157], s[28:29] op_sel_hi:[1,0]
	v_pk_mul_f32 v[158:159], v[158:159], s[28:29] op_sel_hi:[1,0]
	v_pk_mul_f32 v[160:161], v[160:161], s[28:29] op_sel_hi:[1,0]
	v_exp_f32_e32 v154, v154
	v_exp_f32_e32 v155, v155
	v_exp_f32_e32 v156, v156
	v_exp_f32_e32 v157, v157
	v_exp_f32_e32 v158, v158
	v_exp_f32_e32 v159, v159
	v_exp_f32_e32 v160, v160
	v_exp_f32_e32 v161, v161
	v_pk_add_f32 v[154:155], v[154:155], s[0:1] op_sel_hi:[1,0]
	v_pk_add_f32 v[156:157], v[156:157], s[0:1] op_sel_hi:[1,0]
	v_pk_add_f32 v[158:159], v[158:159], s[0:1] op_sel_hi:[1,0]
	v_pk_add_f32 v[160:161], v[160:161], s[0:1] op_sel_hi:[1,0]
	v_rcp_f32_e32 v154, v154
	v_rcp_f32_e32 v155, v155
	v_rcp_f32_e32 v156, v156
	v_rcp_f32_e32 v157, v157
	v_rcp_f32_e32 v158, v158
	v_rcp_f32_e32 v159, v159
	v_rcp_f32_e32 v160, v160
	v_rcp_f32_e32 v161, v161
	v_pk_mul_f32 v[110:111], v[110:111], v[154:155]
	v_pk_mul_f32 v[112:113], v[112:113], v[156:157]
	v_pk_mul_f32 v[106:107], v[106:107], v[158:159]
	v_pk_mul_f32 v[108:109], v[108:109], v[160:161]
	v_add_f32_e32 v193, v193, v110
	v_add_f32_e32 v193, v193, v111
	v_add_f32_e32 v193, v193, v112
	v_add_f32_e32 v193, v193, v113
	v_add_f32_e32 v193, v193, v106
	v_add_f32_e32 v193, v193, v107
	v_add_f32_e32 v193, v193, v108
	v_add_f32_e32 v193, v193, v109
	v_fmac_f32_e32 v225, v110, v110
	v_fmac_f32_e32 v225, v111, v111
	v_fmac_f32_e32 v225, v112, v112
	v_fmac_f32_e32 v225, v113, v113
	v_fmac_f32_e32 v225, v106, v106
	v_fmac_f32_e32 v225, v107, v107
	v_fmac_f32_e32 v225, v108, v108
	v_fmac_f32_e32 v225, v109, v109
	v_cvt_pk_bf16_f32 v130, v110, v111
	v_cvt_pk_bf16_f32 v131, v112, v113
	v_cvt_pk_bf16_f32 v132, v106, v107
	v_cvt_pk_bf16_f32 v133, v108, v109
	ds_write_b16 v167, v130 offset:0
	ds_write_b16_d16_hi v167, v130 offset:32
	ds_write_b16 v167, v131 offset:64
	ds_write_b16_d16_hi v167, v131 offset:96
	ds_write_b16 v167, v132 offset:128
	ds_write_b16_d16_hi v167, v132 offset:160
	ds_write_b16 v167, v133 offset:192
	ds_write_b16_d16_hi v167, v133 offset:224
	v_pk_mul_f32 v[102:103], v[102:103], v[178:179] op_sel_hi:[1,0]
	v_pk_mul_f32 v[104:105], v[104:105], v[178:179] op_sel_hi:[1,0]
	v_pk_mul_f32 v[98:99], v[98:99], v[178:179] op_sel_hi:[1,0]
	v_pk_mul_f32 v[100:101], v[100:101], v[178:179] op_sel_hi:[1,0]
	v_pk_mul_f32 v[154:155], v[102:103], s[2:3] op_sel_hi:[1,0]
	v_pk_mul_f32 v[156:157], v[104:105], s[2:3] op_sel_hi:[1,0]
	v_pk_mul_f32 v[158:159], v[98:99], s[2:3] op_sel_hi:[1,0]
	v_pk_mul_f32 v[160:161], v[100:101], s[2:3] op_sel_hi:[1,0]
	v_pk_mul_f32 v[154:155], v[102:103], v[154:155]
	v_pk_mul_f32 v[156:157], v[104:105], v[156:157]
	v_pk_mul_f32 v[158:159], v[98:99], v[158:159]
	v_pk_mul_f32 v[160:161], v[100:101], v[160:161]
	v_pk_fma_f32 v[154:155], v[102:103], v[154:155], v[102:103]
	v_pk_fma_f32 v[156:157], v[104:105], v[156:157], v[104:105]
	v_pk_fma_f32 v[158:159], v[98:99], v[158:159], v[98:99]
	v_pk_fma_f32 v[160:161], v[100:101], v[160:161], v[100:101]
	v_pk_mul_f32 v[154:155], v[154:155], s[48:49] op_sel_hi:[1,0]
	v_pk_mul_f32 v[156:157], v[156:157], s[48:49] op_sel_hi:[1,0]
	v_pk_mul_f32 v[158:159], v[158:159], s[48:49] op_sel_hi:[1,0]
	v_pk_mul_f32 v[160:161], v[160:161], s[48:49] op_sel_hi:[1,0]
	v_pk_mul_f32 v[154:155], v[154:155], s[28:29] op_sel_hi:[1,0]
	v_pk_mul_f32 v[156:157], v[156:157], s[28:29] op_sel_hi:[1,0]
	v_pk_mul_f32 v[158:159], v[158:159], s[28:29] op_sel_hi:[1,0]
	v_pk_mul_f32 v[160:161], v[160:161], s[28:29] op_sel_hi:[1,0]
	v_exp_f32_e32 v154, v154
	v_exp_f32_e32 v155, v155
	v_exp_f32_e32 v156, v156
	v_exp_f32_e32 v157, v157
	v_exp_f32_e32 v158, v158
	v_exp_f32_e32 v159, v159
	v_exp_f32_e32 v160, v160
	v_exp_f32_e32 v161, v161
	v_pk_add_f32 v[154:155], v[154:155], s[0:1] op_sel_hi:[1,0]
	v_pk_add_f32 v[156:157], v[156:157], s[0:1] op_sel_hi:[1,0]
	v_pk_add_f32 v[158:159], v[158:159], s[0:1] op_sel_hi:[1,0]
	v_pk_add_f32 v[160:161], v[160:161], s[0:1] op_sel_hi:[1,0]
	v_rcp_f32_e32 v154, v154
	v_rcp_f32_e32 v155, v155
	v_rcp_f32_e32 v156, v156
	v_rcp_f32_e32 v157, v157
	v_rcp_f32_e32 v158, v158
	v_rcp_f32_e32 v159, v159
	v_rcp_f32_e32 v160, v160
	v_rcp_f32_e32 v161, v161
	v_pk_mul_f32 v[102:103], v[102:103], v[154:155]
	v_pk_mul_f32 v[104:105], v[104:105], v[156:157]
	v_pk_mul_f32 v[98:99], v[98:99], v[158:159]
	v_pk_mul_f32 v[100:101], v[100:101], v[160:161]
	v_add_f32_e32 v193, v193, v102
	v_add_f32_e32 v193, v193, v103
	v_add_f32_e32 v193, v193, v104
	v_add_f32_e32 v193, v193, v105
	v_add_f32_e32 v193, v193, v98
	v_add_f32_e32 v193, v193, v99
	v_add_f32_e32 v193, v193, v100
	v_add_f32_e32 v193, v193, v101
	v_fmac_f32_e32 v225, v102, v102
	v_fmac_f32_e32 v225, v103, v103
	v_fmac_f32_e32 v225, v104, v104
	v_fmac_f32_e32 v225, v105, v105
	v_fmac_f32_e32 v225, v98, v98
	v_fmac_f32_e32 v225, v99, v99
	v_fmac_f32_e32 v225, v100, v100
	v_fmac_f32_e32 v225, v101, v101
	v_cvt_pk_bf16_f32 v130, v102, v103
	v_cvt_pk_bf16_f32 v131, v104, v105
	v_cvt_pk_bf16_f32 v132, v98, v99
	v_cvt_pk_bf16_f32 v133, v100, v101
	ds_write_b16 v167, v130 offset:8192
	ds_write_b16_d16_hi v167, v130 offset:8224
	ds_write_b16 v167, v131 offset:8256
	ds_write_b16_d16_hi v167, v131 offset:8288
	ds_write_b16 v167, v132 offset:8320
	ds_write_b16_d16_hi v167, v132 offset:8352
	ds_write_b16 v167, v133 offset:8384
	ds_write_b16_d16_hi v167, v133 offset:8416
	s_waitcnt lgkmcnt(0)
	ds_read_b128 v[232:235], v168
	ds_read_b128 v[236:239], v168 offset:16
	s_waitcnt lgkmcnt(0)
	global_store_dwordx4 v165, v[232:235], s[44:45] offset:32
	global_store_dwordx4 v165, v[236:239], s[44:45] offset:48
	v_pk_mul_f32 v[94:95], v[94:95], v[180:181] op_sel_hi:[1,0]
	v_pk_mul_f32 v[96:97], v[96:97], v[180:181] op_sel_hi:[1,0]
	v_pk_mul_f32 v[90:91], v[90:91], v[180:181] op_sel_hi:[1,0]
	v_pk_mul_f32 v[92:93], v[92:93], v[180:181] op_sel_hi:[1,0]
	v_pk_mul_f32 v[154:155], v[94:95], s[2:3] op_sel_hi:[1,0]
	v_pk_mul_f32 v[156:157], v[96:97], s[2:3] op_sel_hi:[1,0]
	v_pk_mul_f32 v[158:159], v[90:91], s[2:3] op_sel_hi:[1,0]
	v_pk_mul_f32 v[160:161], v[92:93], s[2:3] op_sel_hi:[1,0]
	v_pk_mul_f32 v[154:155], v[94:95], v[154:155]
	v_pk_mul_f32 v[156:157], v[96:97], v[156:157]
	v_pk_mul_f32 v[158:159], v[90:91], v[158:159]
	v_pk_mul_f32 v[160:161], v[92:93], v[160:161]
	v_pk_fma_f32 v[154:155], v[94:95], v[154:155], v[94:95]
	v_pk_fma_f32 v[156:157], v[96:97], v[156:157], v[96:97]
	v_pk_fma_f32 v[158:159], v[90:91], v[158:159], v[90:91]
	v_pk_fma_f32 v[160:161], v[92:93], v[160:161], v[92:93]
	v_pk_mul_f32 v[154:155], v[154:155], s[48:49] op_sel_hi:[1,0]
	v_pk_mul_f32 v[156:157], v[156:157], s[48:49] op_sel_hi:[1,0]
	v_pk_mul_f32 v[158:159], v[158:159], s[48:49] op_sel_hi:[1,0]
	v_pk_mul_f32 v[160:161], v[160:161], s[48:49] op_sel_hi:[1,0]
	v_pk_mul_f32 v[154:155], v[154:155], s[28:29] op_sel_hi:[1,0]
	v_pk_mul_f32 v[156:157], v[156:157], s[28:29] op_sel_hi:[1,0]
	v_pk_mul_f32 v[158:159], v[158:159], s[28:29] op_sel_hi:[1,0]
	v_pk_mul_f32 v[160:161], v[160:161], s[28:29] op_sel_hi:[1,0]
	v_exp_f32_e32 v154, v154
	v_exp_f32_e32 v155, v155
	v_exp_f32_e32 v156, v156
	v_exp_f32_e32 v157, v157
	v_exp_f32_e32 v158, v158
	v_exp_f32_e32 v159, v159
	v_exp_f32_e32 v160, v160
	v_exp_f32_e32 v161, v161
	v_pk_add_f32 v[154:155], v[154:155], s[0:1] op_sel_hi:[1,0]
	v_pk_add_f32 v[156:157], v[156:157], s[0:1] op_sel_hi:[1,0]
	v_pk_add_f32 v[158:159], v[158:159], s[0:1] op_sel_hi:[1,0]
	v_pk_add_f32 v[160:161], v[160:161], s[0:1] op_sel_hi:[1,0]
	v_rcp_f32_e32 v154, v154
	v_rcp_f32_e32 v155, v155
	v_rcp_f32_e32 v156, v156
	v_rcp_f32_e32 v157, v157
	v_rcp_f32_e32 v158, v158
	v_rcp_f32_e32 v159, v159
	v_rcp_f32_e32 v160, v160
	v_rcp_f32_e32 v161, v161
	v_pk_mul_f32 v[94:95], v[94:95], v[154:155]
	v_pk_mul_f32 v[96:97], v[96:97], v[156:157]
	v_pk_mul_f32 v[90:91], v[90:91], v[158:159]
	v_pk_mul_f32 v[92:93], v[92:93], v[160:161]
	v_add_f32_e32 v194, v194, v94
	v_add_f32_e32 v194, v194, v95
	v_add_f32_e32 v194, v194, v96
	v_add_f32_e32 v194, v194, v97
	v_add_f32_e32 v194, v194, v90
	v_add_f32_e32 v194, v194, v91
	v_add_f32_e32 v194, v194, v92
	v_add_f32_e32 v194, v194, v93
	v_fmac_f32_e32 v226, v94, v94
	v_fmac_f32_e32 v226, v95, v95
	v_fmac_f32_e32 v226, v96, v96
	v_fmac_f32_e32 v226, v97, v97
	v_fmac_f32_e32 v226, v90, v90
	v_fmac_f32_e32 v226, v91, v91
	v_fmac_f32_e32 v226, v92, v92
	v_fmac_f32_e32 v226, v93, v93
	v_cvt_pk_bf16_f32 v130, v94, v95
	v_cvt_pk_bf16_f32 v131, v96, v97
	v_cvt_pk_bf16_f32 v132, v90, v91
	v_cvt_pk_bf16_f32 v133, v92, v93
	ds_write_b16 v167, v130 offset:0
	ds_write_b16_d16_hi v167, v130 offset:32
	ds_write_b16 v167, v131 offset:64
	ds_write_b16_d16_hi v167, v131 offset:96
	ds_write_b16 v167, v132 offset:128
	ds_write_b16_d16_hi v167, v132 offset:160
	ds_write_b16 v167, v133 offset:192
	ds_write_b16_d16_hi v167, v133 offset:224
	v_pk_mul_f32 v[86:87], v[86:87], v[180:181] op_sel_hi:[1,0]
	v_pk_mul_f32 v[88:89], v[88:89], v[180:181] op_sel_hi:[1,0]
	v_pk_mul_f32 v[82:83], v[82:83], v[180:181] op_sel_hi:[1,0]
	v_pk_mul_f32 v[84:85], v[84:85], v[180:181] op_sel_hi:[1,0]
	v_pk_mul_f32 v[154:155], v[86:87], s[2:3] op_sel_hi:[1,0]
	v_pk_mul_f32 v[156:157], v[88:89], s[2:3] op_sel_hi:[1,0]
	v_pk_mul_f32 v[158:159], v[82:83], s[2:3] op_sel_hi:[1,0]
	v_pk_mul_f32 v[160:161], v[84:85], s[2:3] op_sel_hi:[1,0]
	v_pk_mul_f32 v[154:155], v[86:87], v[154:155]
	v_pk_mul_f32 v[156:157], v[88:89], v[156:157]
	v_pk_mul_f32 v[158:159], v[82:83], v[158:159]
	v_pk_mul_f32 v[160:161], v[84:85], v[160:161]
	v_pk_fma_f32 v[154:155], v[86:87], v[154:155], v[86:87]
	v_pk_fma_f32 v[156:157], v[88:89], v[156:157], v[88:89]
	v_pk_fma_f32 v[158:159], v[82:83], v[158:159], v[82:83]
	v_pk_fma_f32 v[160:161], v[84:85], v[160:161], v[84:85]
	v_pk_mul_f32 v[154:155], v[154:155], s[48:49] op_sel_hi:[1,0]
	v_pk_mul_f32 v[156:157], v[156:157], s[48:49] op_sel_hi:[1,0]
	v_pk_mul_f32 v[158:159], v[158:159], s[48:49] op_sel_hi:[1,0]
	v_pk_mul_f32 v[160:161], v[160:161], s[48:49] op_sel_hi:[1,0]
	v_pk_mul_f32 v[154:155], v[154:155], s[28:29] op_sel_hi:[1,0]
	v_pk_mul_f32 v[156:157], v[156:157], s[28:29] op_sel_hi:[1,0]
	v_pk_mul_f32 v[158:159], v[158:159], s[28:29] op_sel_hi:[1,0]
	v_pk_mul_f32 v[160:161], v[160:161], s[28:29] op_sel_hi:[1,0]
	v_exp_f32_e32 v154, v154
	v_exp_f32_e32 v155, v155
	v_exp_f32_e32 v156, v156
	v_exp_f32_e32 v157, v157
	v_exp_f32_e32 v158, v158
	v_exp_f32_e32 v159, v159
	v_exp_f32_e32 v160, v160
	v_exp_f32_e32 v161, v161
	v_pk_add_f32 v[154:155], v[154:155], s[0:1] op_sel_hi:[1,0]
	v_pk_add_f32 v[156:157], v[156:157], s[0:1] op_sel_hi:[1,0]
	v_pk_add_f32 v[158:159], v[158:159], s[0:1] op_sel_hi:[1,0]
	v_pk_add_f32 v[160:161], v[160:161], s[0:1] op_sel_hi:[1,0]
	v_rcp_f32_e32 v154, v154
	v_rcp_f32_e32 v155, v155
	v_rcp_f32_e32 v156, v156
	v_rcp_f32_e32 v157, v157
	v_rcp_f32_e32 v158, v158
	v_rcp_f32_e32 v159, v159
	v_rcp_f32_e32 v160, v160
	v_rcp_f32_e32 v161, v161
	v_pk_mul_f32 v[86:87], v[86:87], v[154:155]
	v_pk_mul_f32 v[88:89], v[88:89], v[156:157]
	v_pk_mul_f32 v[82:83], v[82:83], v[158:159]
	v_pk_mul_f32 v[84:85], v[84:85], v[160:161]
	v_add_f32_e32 v194, v194, v86
	v_add_f32_e32 v194, v194, v87
	v_add_f32_e32 v194, v194, v88
	v_add_f32_e32 v194, v194, v89
	v_add_f32_e32 v194, v194, v82
	v_add_f32_e32 v194, v194, v83
	v_add_f32_e32 v194, v194, v84
	v_add_f32_e32 v194, v194, v85
	v_fmac_f32_e32 v226, v86, v86
	v_fmac_f32_e32 v226, v87, v87
	v_fmac_f32_e32 v226, v88, v88
	v_fmac_f32_e32 v226, v89, v89
	v_fmac_f32_e32 v226, v82, v82
	v_fmac_f32_e32 v226, v83, v83
	v_fmac_f32_e32 v226, v84, v84
	v_fmac_f32_e32 v226, v85, v85
	v_cvt_pk_bf16_f32 v130, v86, v87
	v_cvt_pk_bf16_f32 v131, v88, v89
	v_cvt_pk_bf16_f32 v132, v82, v83
	v_cvt_pk_bf16_f32 v133, v84, v85
	ds_write_b16 v167, v130 offset:8192
	ds_write_b16_d16_hi v167, v130 offset:8224
	ds_write_b16 v167, v131 offset:8256
	ds_write_b16_d16_hi v167, v131 offset:8288
	ds_write_b16 v167, v132 offset:8320
	ds_write_b16_d16_hi v167, v132 offset:8352
	ds_write_b16 v167, v133 offset:8384
	ds_write_b16_d16_hi v167, v133 offset:8416
	s_waitcnt lgkmcnt(0)
	ds_read_b128 v[232:235], v168
	ds_read_b128 v[236:239], v168 offset:16
	s_waitcnt lgkmcnt(0)
	global_store_dwordx4 v165, v[232:235], s[44:45] offset:64
	global_store_dwordx4 v165, v[236:239], s[44:45] offset:80
	v_pk_mul_f32 v[78:79], v[78:79], v[182:183] op_sel_hi:[1,0]
	v_pk_mul_f32 v[80:81], v[80:81], v[182:183] op_sel_hi:[1,0]
	v_pk_mul_f32 v[74:75], v[74:75], v[182:183] op_sel_hi:[1,0]
	v_pk_mul_f32 v[76:77], v[76:77], v[182:183] op_sel_hi:[1,0]
	v_pk_mul_f32 v[154:155], v[78:79], s[2:3] op_sel_hi:[1,0]
	v_pk_mul_f32 v[156:157], v[80:81], s[2:3] op_sel_hi:[1,0]
	v_pk_mul_f32 v[158:159], v[74:75], s[2:3] op_sel_hi:[1,0]
	v_pk_mul_f32 v[160:161], v[76:77], s[2:3] op_sel_hi:[1,0]
	v_pk_mul_f32 v[154:155], v[78:79], v[154:155]
	v_pk_mul_f32 v[156:157], v[80:81], v[156:157]
	v_pk_mul_f32 v[158:159], v[74:75], v[158:159]
	v_pk_mul_f32 v[160:161], v[76:77], v[160:161]
	v_pk_fma_f32 v[154:155], v[78:79], v[154:155], v[78:79]
	v_pk_fma_f32 v[156:157], v[80:81], v[156:157], v[80:81]
	v_pk_fma_f32 v[158:159], v[74:75], v[158:159], v[74:75]
	v_pk_fma_f32 v[160:161], v[76:77], v[160:161], v[76:77]
	v_pk_mul_f32 v[154:155], v[154:155], s[48:49] op_sel_hi:[1,0]
	v_pk_mul_f32 v[156:157], v[156:157], s[48:49] op_sel_hi:[1,0]
	v_pk_mul_f32 v[158:159], v[158:159], s[48:49] op_sel_hi:[1,0]
	v_pk_mul_f32 v[160:161], v[160:161], s[48:49] op_sel_hi:[1,0]
	v_pk_mul_f32 v[154:155], v[154:155], s[28:29] op_sel_hi:[1,0]
	v_pk_mul_f32 v[156:157], v[156:157], s[28:29] op_sel_hi:[1,0]
	v_pk_mul_f32 v[158:159], v[158:159], s[28:29] op_sel_hi:[1,0]
	v_pk_mul_f32 v[160:161], v[160:161], s[28:29] op_sel_hi:[1,0]
	v_exp_f32_e32 v154, v154
	v_exp_f32_e32 v155, v155
	v_exp_f32_e32 v156, v156
	v_exp_f32_e32 v157, v157
	v_exp_f32_e32 v158, v158
	v_exp_f32_e32 v159, v159
	v_exp_f32_e32 v160, v160
	v_exp_f32_e32 v161, v161
	v_pk_add_f32 v[154:155], v[154:155], s[0:1] op_sel_hi:[1,0]
	v_pk_add_f32 v[156:157], v[156:157], s[0:1] op_sel_hi:[1,0]
	v_pk_add_f32 v[158:159], v[158:159], s[0:1] op_sel_hi:[1,0]
	v_pk_add_f32 v[160:161], v[160:161], s[0:1] op_sel_hi:[1,0]
	v_rcp_f32_e32 v154, v154
	v_rcp_f32_e32 v155, v155
	v_rcp_f32_e32 v156, v156
	v_rcp_f32_e32 v157, v157
	v_rcp_f32_e32 v158, v158
	v_rcp_f32_e32 v159, v159
	v_rcp_f32_e32 v160, v160
	v_rcp_f32_e32 v161, v161
	v_pk_mul_f32 v[78:79], v[78:79], v[154:155]
	v_pk_mul_f32 v[80:81], v[80:81], v[156:157]
	v_pk_mul_f32 v[74:75], v[74:75], v[158:159]
	v_pk_mul_f32 v[76:77], v[76:77], v[160:161]
	v_add_f32_e32 v195, v195, v78
	v_add_f32_e32 v195, v195, v79
	v_add_f32_e32 v195, v195, v80
	v_add_f32_e32 v195, v195, v81
	v_add_f32_e32 v195, v195, v74
	v_add_f32_e32 v195, v195, v75
	v_add_f32_e32 v195, v195, v76
	v_add_f32_e32 v195, v195, v77
	v_fmac_f32_e32 v227, v78, v78
	v_fmac_f32_e32 v227, v79, v79
	v_fmac_f32_e32 v227, v80, v80
	v_fmac_f32_e32 v227, v81, v81
	v_fmac_f32_e32 v227, v74, v74
	v_fmac_f32_e32 v227, v75, v75
	v_fmac_f32_e32 v227, v76, v76
	v_fmac_f32_e32 v227, v77, v77
	v_cvt_pk_bf16_f32 v130, v78, v79
	v_cvt_pk_bf16_f32 v131, v80, v81
	v_cvt_pk_bf16_f32 v132, v74, v75
	v_cvt_pk_bf16_f32 v133, v76, v77
	ds_write_b16 v167, v130 offset:0
	ds_write_b16_d16_hi v167, v130 offset:32
	ds_write_b16 v167, v131 offset:64
	ds_write_b16_d16_hi v167, v131 offset:96
	ds_write_b16 v167, v132 offset:128
	ds_write_b16_d16_hi v167, v132 offset:160
	ds_write_b16 v167, v133 offset:192
	ds_write_b16_d16_hi v167, v133 offset:224
	v_pk_mul_f32 v[70:71], v[70:71], v[182:183] op_sel_hi:[1,0]
	v_pk_mul_f32 v[72:73], v[72:73], v[182:183] op_sel_hi:[1,0]
	v_pk_mul_f32 v[66:67], v[66:67], v[182:183] op_sel_hi:[1,0]
	v_pk_mul_f32 v[68:69], v[68:69], v[182:183] op_sel_hi:[1,0]
	v_pk_mul_f32 v[154:155], v[70:71], s[2:3] op_sel_hi:[1,0]
	v_pk_mul_f32 v[156:157], v[72:73], s[2:3] op_sel_hi:[1,0]
	v_pk_mul_f32 v[158:159], v[66:67], s[2:3] op_sel_hi:[1,0]
	v_pk_mul_f32 v[160:161], v[68:69], s[2:3] op_sel_hi:[1,0]
	v_pk_mul_f32 v[154:155], v[70:71], v[154:155]
	v_pk_mul_f32 v[156:157], v[72:73], v[156:157]
	v_pk_mul_f32 v[158:159], v[66:67], v[158:159]
	v_pk_mul_f32 v[160:161], v[68:69], v[160:161]
	v_pk_fma_f32 v[154:155], v[70:71], v[154:155], v[70:71]
	v_pk_fma_f32 v[156:157], v[72:73], v[156:157], v[72:73]
	v_pk_fma_f32 v[158:159], v[66:67], v[158:159], v[66:67]
	v_pk_fma_f32 v[160:161], v[68:69], v[160:161], v[68:69]
	v_pk_mul_f32 v[154:155], v[154:155], s[48:49] op_sel_hi:[1,0]
	v_pk_mul_f32 v[156:157], v[156:157], s[48:49] op_sel_hi:[1,0]
	v_pk_mul_f32 v[158:159], v[158:159], s[48:49] op_sel_hi:[1,0]
	v_pk_mul_f32 v[160:161], v[160:161], s[48:49] op_sel_hi:[1,0]
	v_pk_mul_f32 v[154:155], v[154:155], s[28:29] op_sel_hi:[1,0]
	v_pk_mul_f32 v[156:157], v[156:157], s[28:29] op_sel_hi:[1,0]
	v_pk_mul_f32 v[158:159], v[158:159], s[28:29] op_sel_hi:[1,0]
	v_pk_mul_f32 v[160:161], v[160:161], s[28:29] op_sel_hi:[1,0]
	v_exp_f32_e32 v154, v154
	v_exp_f32_e32 v155, v155
	v_exp_f32_e32 v156, v156
	v_exp_f32_e32 v157, v157
	v_exp_f32_e32 v158, v158
	v_exp_f32_e32 v159, v159
	v_exp_f32_e32 v160, v160
	v_exp_f32_e32 v161, v161
	v_pk_add_f32 v[154:155], v[154:155], s[0:1] op_sel_hi:[1,0]
	v_pk_add_f32 v[156:157], v[156:157], s[0:1] op_sel_hi:[1,0]
	v_pk_add_f32 v[158:159], v[158:159], s[0:1] op_sel_hi:[1,0]
	v_pk_add_f32 v[160:161], v[160:161], s[0:1] op_sel_hi:[1,0]
	v_rcp_f32_e32 v154, v154
	v_rcp_f32_e32 v155, v155
	v_rcp_f32_e32 v156, v156
	v_rcp_f32_e32 v157, v157
	v_rcp_f32_e32 v158, v158
	v_rcp_f32_e32 v159, v159
	v_rcp_f32_e32 v160, v160
	v_rcp_f32_e32 v161, v161
	v_pk_mul_f32 v[70:71], v[70:71], v[154:155]
	v_pk_mul_f32 v[72:73], v[72:73], v[156:157]
	v_pk_mul_f32 v[66:67], v[66:67], v[158:159]
	v_pk_mul_f32 v[68:69], v[68:69], v[160:161]
	v_add_f32_e32 v195, v195, v70
	v_add_f32_e32 v195, v195, v71
	v_add_f32_e32 v195, v195, v72
	v_add_f32_e32 v195, v195, v73
	v_add_f32_e32 v195, v195, v66
	v_add_f32_e32 v195, v195, v67
	v_add_f32_e32 v195, v195, v68
	v_add_f32_e32 v195, v195, v69
	v_fmac_f32_e32 v227, v70, v70
	v_fmac_f32_e32 v227, v71, v71
	v_fmac_f32_e32 v227, v72, v72
	v_fmac_f32_e32 v227, v73, v73
	v_fmac_f32_e32 v227, v66, v66
	v_fmac_f32_e32 v227, v67, v67
	v_fmac_f32_e32 v227, v68, v68
	v_fmac_f32_e32 v227, v69, v69
	v_cvt_pk_bf16_f32 v130, v70, v71
	v_cvt_pk_bf16_f32 v131, v72, v73
	v_cvt_pk_bf16_f32 v132, v66, v67
	v_cvt_pk_bf16_f32 v133, v68, v69
	ds_write_b16 v167, v130 offset:8192
	ds_write_b16_d16_hi v167, v130 offset:8224
	ds_write_b16 v167, v131 offset:8256
	ds_write_b16_d16_hi v167, v131 offset:8288
	ds_write_b16 v167, v132 offset:8320
	ds_write_b16_d16_hi v167, v132 offset:8352
	ds_write_b16 v167, v133 offset:8384
	ds_write_b16_d16_hi v167, v133 offset:8416
	s_waitcnt lgkmcnt(0)
	ds_read_b128 v[232:235], v168
	ds_read_b128 v[236:239], v168 offset:16
	s_waitcnt lgkmcnt(0)
	global_store_dwordx4 v165, v[232:235], s[44:45] offset:96
	global_store_dwordx4 v165, v[236:239], s[44:45] offset:112
	v_add_u32_e32 v165, 0x40000, v165
	v_pk_mul_f32 v[62:63], v[62:63], v[184:185] op_sel_hi:[1,0]
	v_pk_mul_f32 v[64:65], v[64:65], v[184:185] op_sel_hi:[1,0]
	v_pk_mul_f32 v[58:59], v[58:59], v[184:185] op_sel_hi:[1,0]
	v_pk_mul_f32 v[60:61], v[60:61], v[184:185] op_sel_hi:[1,0]
	v_pk_mul_f32 v[154:155], v[62:63], s[2:3] op_sel_hi:[1,0]
	v_pk_mul_f32 v[156:157], v[64:65], s[2:3] op_sel_hi:[1,0]
	v_pk_mul_f32 v[158:159], v[58:59], s[2:3] op_sel_hi:[1,0]
	v_pk_mul_f32 v[160:161], v[60:61], s[2:3] op_sel_hi:[1,0]
	v_pk_mul_f32 v[154:155], v[62:63], v[154:155]
	v_pk_mul_f32 v[156:157], v[64:65], v[156:157]
	v_pk_mul_f32 v[158:159], v[58:59], v[158:159]
	v_pk_mul_f32 v[160:161], v[60:61], v[160:161]
	v_pk_fma_f32 v[154:155], v[62:63], v[154:155], v[62:63]
	v_pk_fma_f32 v[156:157], v[64:65], v[156:157], v[64:65]
	v_pk_fma_f32 v[158:159], v[58:59], v[158:159], v[58:59]
	v_pk_fma_f32 v[160:161], v[60:61], v[160:161], v[60:61]
	v_pk_mul_f32 v[154:155], v[154:155], s[48:49] op_sel_hi:[1,0]
	v_pk_mul_f32 v[156:157], v[156:157], s[48:49] op_sel_hi:[1,0]
	v_pk_mul_f32 v[158:159], v[158:159], s[48:49] op_sel_hi:[1,0]
	v_pk_mul_f32 v[160:161], v[160:161], s[48:49] op_sel_hi:[1,0]
	v_pk_mul_f32 v[154:155], v[154:155], s[28:29] op_sel_hi:[1,0]
	v_pk_mul_f32 v[156:157], v[156:157], s[28:29] op_sel_hi:[1,0]
	v_pk_mul_f32 v[158:159], v[158:159], s[28:29] op_sel_hi:[1,0]
	v_pk_mul_f32 v[160:161], v[160:161], s[28:29] op_sel_hi:[1,0]
	v_exp_f32_e32 v154, v154
	v_exp_f32_e32 v155, v155
	v_exp_f32_e32 v156, v156
	v_exp_f32_e32 v157, v157
	v_exp_f32_e32 v158, v158
	v_exp_f32_e32 v159, v159
	v_exp_f32_e32 v160, v160
	v_exp_f32_e32 v161, v161
	v_pk_add_f32 v[154:155], v[154:155], s[0:1] op_sel_hi:[1,0]
	v_pk_add_f32 v[156:157], v[156:157], s[0:1] op_sel_hi:[1,0]
	v_pk_add_f32 v[158:159], v[158:159], s[0:1] op_sel_hi:[1,0]
	v_pk_add_f32 v[160:161], v[160:161], s[0:1] op_sel_hi:[1,0]
	v_rcp_f32_e32 v154, v154
	v_rcp_f32_e32 v155, v155
	v_rcp_f32_e32 v156, v156
	v_rcp_f32_e32 v157, v157
	v_rcp_f32_e32 v158, v158
	v_rcp_f32_e32 v159, v159
	v_rcp_f32_e32 v160, v160
	v_rcp_f32_e32 v161, v161
	v_pk_mul_f32 v[62:63], v[62:63], v[154:155]
	v_pk_mul_f32 v[64:65], v[64:65], v[156:157]
	v_pk_mul_f32 v[58:59], v[58:59], v[158:159]
	v_pk_mul_f32 v[60:61], v[60:61], v[160:161]
	v_add_f32_e32 v196, v196, v62
	v_add_f32_e32 v196, v196, v63
	v_add_f32_e32 v196, v196, v64
	v_add_f32_e32 v196, v196, v65
	v_add_f32_e32 v196, v196, v58
	v_add_f32_e32 v196, v196, v59
	v_add_f32_e32 v196, v196, v60
	v_add_f32_e32 v196, v196, v61
	v_fmac_f32_e32 v228, v62, v62
	v_fmac_f32_e32 v228, v63, v63
	v_fmac_f32_e32 v228, v64, v64
	v_fmac_f32_e32 v228, v65, v65
	v_fmac_f32_e32 v228, v58, v58
	v_fmac_f32_e32 v228, v59, v59
	v_fmac_f32_e32 v228, v60, v60
	v_fmac_f32_e32 v228, v61, v61
	v_cvt_pk_bf16_f32 v130, v62, v63
	v_cvt_pk_bf16_f32 v131, v64, v65
	v_cvt_pk_bf16_f32 v132, v58, v59
	v_cvt_pk_bf16_f32 v133, v60, v61
	ds_write_b16 v167, v130 offset:0
	ds_write_b16_d16_hi v167, v130 offset:32
	ds_write_b16 v167, v131 offset:64
	ds_write_b16_d16_hi v167, v131 offset:96
	ds_write_b16 v167, v132 offset:128
	ds_write_b16_d16_hi v167, v132 offset:160
	ds_write_b16 v167, v133 offset:192
	ds_write_b16_d16_hi v167, v133 offset:224
	v_pk_mul_f32 v[54:55], v[54:55], v[184:185] op_sel_hi:[1,0]
	v_pk_mul_f32 v[56:57], v[56:57], v[184:185] op_sel_hi:[1,0]
	v_pk_mul_f32 v[50:51], v[50:51], v[184:185] op_sel_hi:[1,0]
	v_pk_mul_f32 v[52:53], v[52:53], v[184:185] op_sel_hi:[1,0]
	v_pk_mul_f32 v[154:155], v[54:55], s[2:3] op_sel_hi:[1,0]
	v_pk_mul_f32 v[156:157], v[56:57], s[2:3] op_sel_hi:[1,0]
	v_pk_mul_f32 v[158:159], v[50:51], s[2:3] op_sel_hi:[1,0]
	v_pk_mul_f32 v[160:161], v[52:53], s[2:3] op_sel_hi:[1,0]
	v_pk_mul_f32 v[154:155], v[54:55], v[154:155]
	v_pk_mul_f32 v[156:157], v[56:57], v[156:157]
	v_pk_mul_f32 v[158:159], v[50:51], v[158:159]
	v_pk_mul_f32 v[160:161], v[52:53], v[160:161]
	v_pk_fma_f32 v[154:155], v[54:55], v[154:155], v[54:55]
	v_pk_fma_f32 v[156:157], v[56:57], v[156:157], v[56:57]
	v_pk_fma_f32 v[158:159], v[50:51], v[158:159], v[50:51]
	v_pk_fma_f32 v[160:161], v[52:53], v[160:161], v[52:53]
	v_pk_mul_f32 v[154:155], v[154:155], s[48:49] op_sel_hi:[1,0]
	v_pk_mul_f32 v[156:157], v[156:157], s[48:49] op_sel_hi:[1,0]
	v_pk_mul_f32 v[158:159], v[158:159], s[48:49] op_sel_hi:[1,0]
	v_pk_mul_f32 v[160:161], v[160:161], s[48:49] op_sel_hi:[1,0]
	v_pk_mul_f32 v[154:155], v[154:155], s[28:29] op_sel_hi:[1,0]
	v_pk_mul_f32 v[156:157], v[156:157], s[28:29] op_sel_hi:[1,0]
	v_pk_mul_f32 v[158:159], v[158:159], s[28:29] op_sel_hi:[1,0]
	v_pk_mul_f32 v[160:161], v[160:161], s[28:29] op_sel_hi:[1,0]
	v_exp_f32_e32 v154, v154
	v_exp_f32_e32 v155, v155
	v_exp_f32_e32 v156, v156
	v_exp_f32_e32 v157, v157
	v_exp_f32_e32 v158, v158
	v_exp_f32_e32 v159, v159
	v_exp_f32_e32 v160, v160
	v_exp_f32_e32 v161, v161
	v_pk_add_f32 v[154:155], v[154:155], s[0:1] op_sel_hi:[1,0]
	v_pk_add_f32 v[156:157], v[156:157], s[0:1] op_sel_hi:[1,0]
	v_pk_add_f32 v[158:159], v[158:159], s[0:1] op_sel_hi:[1,0]
	v_pk_add_f32 v[160:161], v[160:161], s[0:1] op_sel_hi:[1,0]
	v_rcp_f32_e32 v154, v154
	v_rcp_f32_e32 v155, v155
	v_rcp_f32_e32 v156, v156
	v_rcp_f32_e32 v157, v157
	v_rcp_f32_e32 v158, v158
	v_rcp_f32_e32 v159, v159
	v_rcp_f32_e32 v160, v160
	v_rcp_f32_e32 v161, v161
	v_pk_mul_f32 v[54:55], v[54:55], v[154:155]
	v_pk_mul_f32 v[56:57], v[56:57], v[156:157]
	v_pk_mul_f32 v[50:51], v[50:51], v[158:159]
	v_pk_mul_f32 v[52:53], v[52:53], v[160:161]
	v_add_f32_e32 v196, v196, v54
	v_add_f32_e32 v196, v196, v55
	v_add_f32_e32 v196, v196, v56
	v_add_f32_e32 v196, v196, v57
	v_add_f32_e32 v196, v196, v50
	v_add_f32_e32 v196, v196, v51
	v_add_f32_e32 v196, v196, v52
	v_add_f32_e32 v196, v196, v53
	v_fmac_f32_e32 v228, v54, v54
	v_fmac_f32_e32 v228, v55, v55
	v_fmac_f32_e32 v228, v56, v56
	v_fmac_f32_e32 v228, v57, v57
	v_fmac_f32_e32 v228, v50, v50
	v_fmac_f32_e32 v228, v51, v51
	v_fmac_f32_e32 v228, v52, v52
	v_fmac_f32_e32 v228, v53, v53
	v_cvt_pk_bf16_f32 v130, v54, v55
	v_cvt_pk_bf16_f32 v131, v56, v57
	v_cvt_pk_bf16_f32 v132, v50, v51
	v_cvt_pk_bf16_f32 v133, v52, v53
	ds_write_b16 v167, v130 offset:8192
	ds_write_b16_d16_hi v167, v130 offset:8224
	ds_write_b16 v167, v131 offset:8256
	ds_write_b16_d16_hi v167, v131 offset:8288
	ds_write_b16 v167, v132 offset:8320
	ds_write_b16_d16_hi v167, v132 offset:8352
	ds_write_b16 v167, v133 offset:8384
	ds_write_b16_d16_hi v167, v133 offset:8416
	s_waitcnt lgkmcnt(0)
	ds_read_b128 v[232:235], v168
	ds_read_b128 v[236:239], v168 offset:16
	s_waitcnt lgkmcnt(0)
	global_store_dwordx4 v165, v[232:235], s[44:45]
	global_store_dwordx4 v165, v[236:239], s[44:45] offset:16
	v_pk_mul_f32 v[46:47], v[46:47], v[186:187] op_sel_hi:[1,0]
	v_pk_mul_f32 v[48:49], v[48:49], v[186:187] op_sel_hi:[1,0]
	v_pk_mul_f32 v[42:43], v[42:43], v[186:187] op_sel_hi:[1,0]
	v_pk_mul_f32 v[44:45], v[44:45], v[186:187] op_sel_hi:[1,0]
	v_pk_mul_f32 v[154:155], v[46:47], s[2:3] op_sel_hi:[1,0]
	v_pk_mul_f32 v[156:157], v[48:49], s[2:3] op_sel_hi:[1,0]
	v_pk_mul_f32 v[158:159], v[42:43], s[2:3] op_sel_hi:[1,0]
	v_pk_mul_f32 v[160:161], v[44:45], s[2:3] op_sel_hi:[1,0]
	v_pk_mul_f32 v[154:155], v[46:47], v[154:155]
	v_pk_mul_f32 v[156:157], v[48:49], v[156:157]
	v_pk_mul_f32 v[158:159], v[42:43], v[158:159]
	v_pk_mul_f32 v[160:161], v[44:45], v[160:161]
	v_pk_fma_f32 v[154:155], v[46:47], v[154:155], v[46:47]
	v_pk_fma_f32 v[156:157], v[48:49], v[156:157], v[48:49]
	v_pk_fma_f32 v[158:159], v[42:43], v[158:159], v[42:43]
	v_pk_fma_f32 v[160:161], v[44:45], v[160:161], v[44:45]
	v_pk_mul_f32 v[154:155], v[154:155], s[48:49] op_sel_hi:[1,0]
	v_pk_mul_f32 v[156:157], v[156:157], s[48:49] op_sel_hi:[1,0]
	v_pk_mul_f32 v[158:159], v[158:159], s[48:49] op_sel_hi:[1,0]
	v_pk_mul_f32 v[160:161], v[160:161], s[48:49] op_sel_hi:[1,0]
	v_pk_mul_f32 v[154:155], v[154:155], s[28:29] op_sel_hi:[1,0]
	v_pk_mul_f32 v[156:157], v[156:157], s[28:29] op_sel_hi:[1,0]
	v_pk_mul_f32 v[158:159], v[158:159], s[28:29] op_sel_hi:[1,0]
	v_pk_mul_f32 v[160:161], v[160:161], s[28:29] op_sel_hi:[1,0]
	v_exp_f32_e32 v154, v154
	v_exp_f32_e32 v155, v155
	v_exp_f32_e32 v156, v156
	v_exp_f32_e32 v157, v157
	v_exp_f32_e32 v158, v158
	v_exp_f32_e32 v159, v159
	v_exp_f32_e32 v160, v160
	v_exp_f32_e32 v161, v161
	v_pk_add_f32 v[154:155], v[154:155], s[0:1] op_sel_hi:[1,0]
	v_pk_add_f32 v[156:157], v[156:157], s[0:1] op_sel_hi:[1,0]
	v_pk_add_f32 v[158:159], v[158:159], s[0:1] op_sel_hi:[1,0]
	v_pk_add_f32 v[160:161], v[160:161], s[0:1] op_sel_hi:[1,0]
	v_rcp_f32_e32 v154, v154
	v_rcp_f32_e32 v155, v155
	v_rcp_f32_e32 v156, v156
	v_rcp_f32_e32 v157, v157
	v_rcp_f32_e32 v158, v158
	v_rcp_f32_e32 v159, v159
	v_rcp_f32_e32 v160, v160
	v_rcp_f32_e32 v161, v161
	v_pk_mul_f32 v[46:47], v[46:47], v[154:155]
	v_pk_mul_f32 v[48:49], v[48:49], v[156:157]
	v_pk_mul_f32 v[42:43], v[42:43], v[158:159]
	v_pk_mul_f32 v[44:45], v[44:45], v[160:161]
	v_add_f32_e32 v197, v197, v46
	v_add_f32_e32 v197, v197, v47
	v_add_f32_e32 v197, v197, v48
	v_add_f32_e32 v197, v197, v49
	v_add_f32_e32 v197, v197, v42
	v_add_f32_e32 v197, v197, v43
	v_add_f32_e32 v197, v197, v44
	v_add_f32_e32 v197, v197, v45
	v_fmac_f32_e32 v229, v46, v46
	v_fmac_f32_e32 v229, v47, v47
	v_fmac_f32_e32 v229, v48, v48
	v_fmac_f32_e32 v229, v49, v49
	v_fmac_f32_e32 v229, v42, v42
	v_fmac_f32_e32 v229, v43, v43
	v_fmac_f32_e32 v229, v44, v44
	v_fmac_f32_e32 v229, v45, v45
	v_cvt_pk_bf16_f32 v130, v46, v47
	v_cvt_pk_bf16_f32 v131, v48, v49
	v_cvt_pk_bf16_f32 v132, v42, v43
	v_cvt_pk_bf16_f32 v133, v44, v45
	ds_write_b16 v167, v130 offset:0
	ds_write_b16_d16_hi v167, v130 offset:32
	ds_write_b16 v167, v131 offset:64
	ds_write_b16_d16_hi v167, v131 offset:96
	ds_write_b16 v167, v132 offset:128
	ds_write_b16_d16_hi v167, v132 offset:160
	ds_write_b16 v167, v133 offset:192
	ds_write_b16_d16_hi v167, v133 offset:224
	v_pk_mul_f32 v[38:39], v[38:39], v[186:187] op_sel_hi:[1,0]
	v_pk_mul_f32 v[40:41], v[40:41], v[186:187] op_sel_hi:[1,0]
	v_pk_mul_f32 v[34:35], v[34:35], v[186:187] op_sel_hi:[1,0]
	v_pk_mul_f32 v[36:37], v[36:37], v[186:187] op_sel_hi:[1,0]
	v_pk_mul_f32 v[154:155], v[38:39], s[2:3] op_sel_hi:[1,0]
	v_pk_mul_f32 v[156:157], v[40:41], s[2:3] op_sel_hi:[1,0]
	v_pk_mul_f32 v[158:159], v[34:35], s[2:3] op_sel_hi:[1,0]
	v_pk_mul_f32 v[160:161], v[36:37], s[2:3] op_sel_hi:[1,0]
	v_pk_mul_f32 v[154:155], v[38:39], v[154:155]
	v_pk_mul_f32 v[156:157], v[40:41], v[156:157]
	v_pk_mul_f32 v[158:159], v[34:35], v[158:159]
	v_pk_mul_f32 v[160:161], v[36:37], v[160:161]
	v_pk_fma_f32 v[154:155], v[38:39], v[154:155], v[38:39]
	v_pk_fma_f32 v[156:157], v[40:41], v[156:157], v[40:41]
	v_pk_fma_f32 v[158:159], v[34:35], v[158:159], v[34:35]
	v_pk_fma_f32 v[160:161], v[36:37], v[160:161], v[36:37]
	v_pk_mul_f32 v[154:155], v[154:155], s[48:49] op_sel_hi:[1,0]
	v_pk_mul_f32 v[156:157], v[156:157], s[48:49] op_sel_hi:[1,0]
	v_pk_mul_f32 v[158:159], v[158:159], s[48:49] op_sel_hi:[1,0]
	v_pk_mul_f32 v[160:161], v[160:161], s[48:49] op_sel_hi:[1,0]
	v_pk_mul_f32 v[154:155], v[154:155], s[28:29] op_sel_hi:[1,0]
	v_pk_mul_f32 v[156:157], v[156:157], s[28:29] op_sel_hi:[1,0]
	v_pk_mul_f32 v[158:159], v[158:159], s[28:29] op_sel_hi:[1,0]
	v_pk_mul_f32 v[160:161], v[160:161], s[28:29] op_sel_hi:[1,0]
	v_exp_f32_e32 v154, v154
	v_exp_f32_e32 v155, v155
	v_exp_f32_e32 v156, v156
	v_exp_f32_e32 v157, v157
	v_exp_f32_e32 v158, v158
	v_exp_f32_e32 v159, v159
	v_exp_f32_e32 v160, v160
	v_exp_f32_e32 v161, v161
	v_pk_add_f32 v[154:155], v[154:155], s[0:1] op_sel_hi:[1,0]
	v_pk_add_f32 v[156:157], v[156:157], s[0:1] op_sel_hi:[1,0]
	v_pk_add_f32 v[158:159], v[158:159], s[0:1] op_sel_hi:[1,0]
	v_pk_add_f32 v[160:161], v[160:161], s[0:1] op_sel_hi:[1,0]
	v_rcp_f32_e32 v154, v154
	v_rcp_f32_e32 v155, v155
	v_rcp_f32_e32 v156, v156
	v_rcp_f32_e32 v157, v157
	v_rcp_f32_e32 v158, v158
	v_rcp_f32_e32 v159, v159
	v_rcp_f32_e32 v160, v160
	v_rcp_f32_e32 v161, v161
	v_pk_mul_f32 v[38:39], v[38:39], v[154:155]
	v_pk_mul_f32 v[40:41], v[40:41], v[156:157]
	v_pk_mul_f32 v[34:35], v[34:35], v[158:159]
	v_pk_mul_f32 v[36:37], v[36:37], v[160:161]
	v_add_f32_e32 v197, v197, v38
	v_add_f32_e32 v197, v197, v39
	v_add_f32_e32 v197, v197, v40
	v_add_f32_e32 v197, v197, v41
	v_add_f32_e32 v197, v197, v34
	v_add_f32_e32 v197, v197, v35
	v_add_f32_e32 v197, v197, v36
	v_add_f32_e32 v197, v197, v37
	v_fmac_f32_e32 v229, v38, v38
	v_fmac_f32_e32 v229, v39, v39
	v_fmac_f32_e32 v229, v40, v40
	v_fmac_f32_e32 v229, v41, v41
	v_fmac_f32_e32 v229, v34, v34
	v_fmac_f32_e32 v229, v35, v35
	v_fmac_f32_e32 v229, v36, v36
	v_fmac_f32_e32 v229, v37, v37
	v_cvt_pk_bf16_f32 v130, v38, v39
	v_cvt_pk_bf16_f32 v131, v40, v41
	v_cvt_pk_bf16_f32 v132, v34, v35
	v_cvt_pk_bf16_f32 v133, v36, v37
	ds_write_b16 v167, v130 offset:8192
	ds_write_b16_d16_hi v167, v130 offset:8224
	ds_write_b16 v167, v131 offset:8256
	ds_write_b16_d16_hi v167, v131 offset:8288
	ds_write_b16 v167, v132 offset:8320
	ds_write_b16_d16_hi v167, v132 offset:8352
	ds_write_b16 v167, v133 offset:8384
	ds_write_b16_d16_hi v167, v133 offset:8416
	s_waitcnt lgkmcnt(0)
	ds_read_b128 v[232:235], v168
	ds_read_b128 v[236:239], v168 offset:16
	s_waitcnt lgkmcnt(0)
	global_store_dwordx4 v165, v[232:235], s[44:45] offset:32
	global_store_dwordx4 v165, v[236:239], s[44:45] offset:48
	v_pk_mul_f32 v[30:31], v[30:31], v[188:189] op_sel_hi:[1,0]
	v_pk_mul_f32 v[32:33], v[32:33], v[188:189] op_sel_hi:[1,0]
	v_pk_mul_f32 v[26:27], v[26:27], v[188:189] op_sel_hi:[1,0]
	v_pk_mul_f32 v[28:29], v[28:29], v[188:189] op_sel_hi:[1,0]
	v_pk_mul_f32 v[154:155], v[30:31], s[2:3] op_sel_hi:[1,0]
	v_pk_mul_f32 v[156:157], v[32:33], s[2:3] op_sel_hi:[1,0]
	v_pk_mul_f32 v[158:159], v[26:27], s[2:3] op_sel_hi:[1,0]
	v_pk_mul_f32 v[160:161], v[28:29], s[2:3] op_sel_hi:[1,0]
	v_pk_mul_f32 v[154:155], v[30:31], v[154:155]
	v_pk_mul_f32 v[156:157], v[32:33], v[156:157]
	v_pk_mul_f32 v[158:159], v[26:27], v[158:159]
	v_pk_mul_f32 v[160:161], v[28:29], v[160:161]
	v_pk_fma_f32 v[154:155], v[30:31], v[154:155], v[30:31]
	v_pk_fma_f32 v[156:157], v[32:33], v[156:157], v[32:33]
	v_pk_fma_f32 v[158:159], v[26:27], v[158:159], v[26:27]
	v_pk_fma_f32 v[160:161], v[28:29], v[160:161], v[28:29]
	v_pk_mul_f32 v[154:155], v[154:155], s[48:49] op_sel_hi:[1,0]
	v_pk_mul_f32 v[156:157], v[156:157], s[48:49] op_sel_hi:[1,0]
	v_pk_mul_f32 v[158:159], v[158:159], s[48:49] op_sel_hi:[1,0]
	v_pk_mul_f32 v[160:161], v[160:161], s[48:49] op_sel_hi:[1,0]
	v_pk_mul_f32 v[154:155], v[154:155], s[28:29] op_sel_hi:[1,0]
	v_pk_mul_f32 v[156:157], v[156:157], s[28:29] op_sel_hi:[1,0]
	v_pk_mul_f32 v[158:159], v[158:159], s[28:29] op_sel_hi:[1,0]
	v_pk_mul_f32 v[160:161], v[160:161], s[28:29] op_sel_hi:[1,0]
	v_exp_f32_e32 v154, v154
	v_exp_f32_e32 v155, v155
	v_exp_f32_e32 v156, v156
	v_exp_f32_e32 v157, v157
	v_exp_f32_e32 v158, v158
	v_exp_f32_e32 v159, v159
	v_exp_f32_e32 v160, v160
	v_exp_f32_e32 v161, v161
	v_pk_add_f32 v[154:155], v[154:155], s[0:1] op_sel_hi:[1,0]
	v_pk_add_f32 v[156:157], v[156:157], s[0:1] op_sel_hi:[1,0]
	v_pk_add_f32 v[158:159], v[158:159], s[0:1] op_sel_hi:[1,0]
	v_pk_add_f32 v[160:161], v[160:161], s[0:1] op_sel_hi:[1,0]
	v_rcp_f32_e32 v154, v154
	v_rcp_f32_e32 v155, v155
	v_rcp_f32_e32 v156, v156
	v_rcp_f32_e32 v157, v157
	v_rcp_f32_e32 v158, v158
	v_rcp_f32_e32 v159, v159
	v_rcp_f32_e32 v160, v160
	v_rcp_f32_e32 v161, v161
	v_pk_mul_f32 v[30:31], v[30:31], v[154:155]
	v_pk_mul_f32 v[32:33], v[32:33], v[156:157]
	v_pk_mul_f32 v[26:27], v[26:27], v[158:159]
	v_pk_mul_f32 v[28:29], v[28:29], v[160:161]
	v_add_f32_e32 v198, v198, v30
	v_add_f32_e32 v198, v198, v31
	v_add_f32_e32 v198, v198, v32
	v_add_f32_e32 v198, v198, v33
	v_add_f32_e32 v198, v198, v26
	v_add_f32_e32 v198, v198, v27
	v_add_f32_e32 v198, v198, v28
	v_add_f32_e32 v198, v198, v29
	v_fmac_f32_e32 v230, v30, v30
	v_fmac_f32_e32 v230, v31, v31
	v_fmac_f32_e32 v230, v32, v32
	v_fmac_f32_e32 v230, v33, v33
	v_fmac_f32_e32 v230, v26, v26
	v_fmac_f32_e32 v230, v27, v27
	v_fmac_f32_e32 v230, v28, v28
	v_fmac_f32_e32 v230, v29, v29
	v_cvt_pk_bf16_f32 v130, v30, v31
	v_cvt_pk_bf16_f32 v131, v32, v33
	v_cvt_pk_bf16_f32 v132, v26, v27
	v_cvt_pk_bf16_f32 v133, v28, v29
	ds_write_b16 v167, v130 offset:0
	ds_write_b16_d16_hi v167, v130 offset:32
	ds_write_b16 v167, v131 offset:64
	ds_write_b16_d16_hi v167, v131 offset:96
	ds_write_b16 v167, v132 offset:128
	ds_write_b16_d16_hi v167, v132 offset:160
	ds_write_b16 v167, v133 offset:192
	ds_write_b16_d16_hi v167, v133 offset:224
	v_pk_mul_f32 v[22:23], v[22:23], v[188:189] op_sel_hi:[1,0]
	v_pk_mul_f32 v[24:25], v[24:25], v[188:189] op_sel_hi:[1,0]
	v_pk_mul_f32 v[18:19], v[18:19], v[188:189] op_sel_hi:[1,0]
	v_pk_mul_f32 v[20:21], v[20:21], v[188:189] op_sel_hi:[1,0]
	v_pk_mul_f32 v[154:155], v[22:23], s[2:3] op_sel_hi:[1,0]
	v_pk_mul_f32 v[156:157], v[24:25], s[2:3] op_sel_hi:[1,0]
	v_pk_mul_f32 v[158:159], v[18:19], s[2:3] op_sel_hi:[1,0]
	v_pk_mul_f32 v[160:161], v[20:21], s[2:3] op_sel_hi:[1,0]
	v_pk_mul_f32 v[154:155], v[22:23], v[154:155]
	v_pk_mul_f32 v[156:157], v[24:25], v[156:157]
	v_pk_mul_f32 v[158:159], v[18:19], v[158:159]
	v_pk_mul_f32 v[160:161], v[20:21], v[160:161]
	v_pk_fma_f32 v[154:155], v[22:23], v[154:155], v[22:23]
	v_pk_fma_f32 v[156:157], v[24:25], v[156:157], v[24:25]
	v_pk_fma_f32 v[158:159], v[18:19], v[158:159], v[18:19]
	v_pk_fma_f32 v[160:161], v[20:21], v[160:161], v[20:21]
	v_pk_mul_f32 v[154:155], v[154:155], s[48:49] op_sel_hi:[1,0]
	v_pk_mul_f32 v[156:157], v[156:157], s[48:49] op_sel_hi:[1,0]
	v_pk_mul_f32 v[158:159], v[158:159], s[48:49] op_sel_hi:[1,0]
	v_pk_mul_f32 v[160:161], v[160:161], s[48:49] op_sel_hi:[1,0]
	v_pk_mul_f32 v[154:155], v[154:155], s[28:29] op_sel_hi:[1,0]
	v_pk_mul_f32 v[156:157], v[156:157], s[28:29] op_sel_hi:[1,0]
	v_pk_mul_f32 v[158:159], v[158:159], s[28:29] op_sel_hi:[1,0]
	v_pk_mul_f32 v[160:161], v[160:161], s[28:29] op_sel_hi:[1,0]
	v_exp_f32_e32 v154, v154
	v_exp_f32_e32 v155, v155
	v_exp_f32_e32 v156, v156
	v_exp_f32_e32 v157, v157
	v_exp_f32_e32 v158, v158
	v_exp_f32_e32 v159, v159
	v_exp_f32_e32 v160, v160
	v_exp_f32_e32 v161, v161
	v_pk_add_f32 v[154:155], v[154:155], s[0:1] op_sel_hi:[1,0]
	v_pk_add_f32 v[156:157], v[156:157], s[0:1] op_sel_hi:[1,0]
	v_pk_add_f32 v[158:159], v[158:159], s[0:1] op_sel_hi:[1,0]
	v_pk_add_f32 v[160:161], v[160:161], s[0:1] op_sel_hi:[1,0]
	v_rcp_f32_e32 v154, v154
	v_rcp_f32_e32 v155, v155
	v_rcp_f32_e32 v156, v156
	v_rcp_f32_e32 v157, v157
	v_rcp_f32_e32 v158, v158
	v_rcp_f32_e32 v159, v159
	v_rcp_f32_e32 v160, v160
	v_rcp_f32_e32 v161, v161
	v_pk_mul_f32 v[22:23], v[22:23], v[154:155]
	v_pk_mul_f32 v[24:25], v[24:25], v[156:157]
	v_pk_mul_f32 v[18:19], v[18:19], v[158:159]
	v_pk_mul_f32 v[20:21], v[20:21], v[160:161]
	v_add_f32_e32 v198, v198, v22
	v_add_f32_e32 v198, v198, v23
	v_add_f32_e32 v198, v198, v24
	v_add_f32_e32 v198, v198, v25
	v_add_f32_e32 v198, v198, v18
	v_add_f32_e32 v198, v198, v19
	v_add_f32_e32 v198, v198, v20
	v_add_f32_e32 v198, v198, v21
	v_fmac_f32_e32 v230, v22, v22
	v_fmac_f32_e32 v230, v23, v23
	v_fmac_f32_e32 v230, v24, v24
	v_fmac_f32_e32 v230, v25, v25
	v_fmac_f32_e32 v230, v18, v18
	v_fmac_f32_e32 v230, v19, v19
	v_fmac_f32_e32 v230, v20, v20
	v_fmac_f32_e32 v230, v21, v21
	v_cvt_pk_bf16_f32 v130, v22, v23
	v_cvt_pk_bf16_f32 v131, v24, v25
	v_cvt_pk_bf16_f32 v132, v18, v19
	v_cvt_pk_bf16_f32 v133, v20, v21
	ds_write_b16 v167, v130 offset:8192
	ds_write_b16_d16_hi v167, v130 offset:8224
	ds_write_b16 v167, v131 offset:8256
	ds_write_b16_d16_hi v167, v131 offset:8288
	ds_write_b16 v167, v132 offset:8320
	ds_write_b16_d16_hi v167, v132 offset:8352
	ds_write_b16 v167, v133 offset:8384
	ds_write_b16_d16_hi v167, v133 offset:8416
	s_waitcnt lgkmcnt(0)
	ds_read_b128 v[232:235], v168
	ds_read_b128 v[236:239], v168 offset:16
	s_waitcnt lgkmcnt(0)
	global_store_dwordx4 v165, v[232:235], s[44:45] offset:64
	global_store_dwordx4 v165, v[236:239], s[44:45] offset:80
	v_pk_mul_f32 v[14:15], v[14:15], v[190:191] op_sel_hi:[1,0]
	v_pk_mul_f32 v[16:17], v[16:17], v[190:191] op_sel_hi:[1,0]
	v_pk_mul_f32 v[10:11], v[10:11], v[190:191] op_sel_hi:[1,0]
	v_pk_mul_f32 v[12:13], v[12:13], v[190:191] op_sel_hi:[1,0]
	v_pk_mul_f32 v[154:155], v[14:15], s[2:3] op_sel_hi:[1,0]
	v_pk_mul_f32 v[156:157], v[16:17], s[2:3] op_sel_hi:[1,0]
	v_pk_mul_f32 v[158:159], v[10:11], s[2:3] op_sel_hi:[1,0]
	v_pk_mul_f32 v[160:161], v[12:13], s[2:3] op_sel_hi:[1,0]
	v_pk_mul_f32 v[154:155], v[14:15], v[154:155]
	v_pk_mul_f32 v[156:157], v[16:17], v[156:157]
	v_pk_mul_f32 v[158:159], v[10:11], v[158:159]
	v_pk_mul_f32 v[160:161], v[12:13], v[160:161]
	v_pk_fma_f32 v[154:155], v[14:15], v[154:155], v[14:15]
	v_pk_fma_f32 v[156:157], v[16:17], v[156:157], v[16:17]
	v_pk_fma_f32 v[158:159], v[10:11], v[158:159], v[10:11]
	v_pk_fma_f32 v[160:161], v[12:13], v[160:161], v[12:13]
	v_pk_mul_f32 v[154:155], v[154:155], s[48:49] op_sel_hi:[1,0]
	v_pk_mul_f32 v[156:157], v[156:157], s[48:49] op_sel_hi:[1,0]
	v_pk_mul_f32 v[158:159], v[158:159], s[48:49] op_sel_hi:[1,0]
	v_pk_mul_f32 v[160:161], v[160:161], s[48:49] op_sel_hi:[1,0]
	v_pk_mul_f32 v[154:155], v[154:155], s[28:29] op_sel_hi:[1,0]
	v_pk_mul_f32 v[156:157], v[156:157], s[28:29] op_sel_hi:[1,0]
	v_pk_mul_f32 v[158:159], v[158:159], s[28:29] op_sel_hi:[1,0]
	v_pk_mul_f32 v[160:161], v[160:161], s[28:29] op_sel_hi:[1,0]
	v_exp_f32_e32 v154, v154
	v_exp_f32_e32 v155, v155
	v_exp_f32_e32 v156, v156
	v_exp_f32_e32 v157, v157
	v_exp_f32_e32 v158, v158
	v_exp_f32_e32 v159, v159
	v_exp_f32_e32 v160, v160
	v_exp_f32_e32 v161, v161
	v_pk_add_f32 v[154:155], v[154:155], s[0:1] op_sel_hi:[1,0]
	v_pk_add_f32 v[156:157], v[156:157], s[0:1] op_sel_hi:[1,0]
	v_pk_add_f32 v[158:159], v[158:159], s[0:1] op_sel_hi:[1,0]
	v_pk_add_f32 v[160:161], v[160:161], s[0:1] op_sel_hi:[1,0]
	v_rcp_f32_e32 v154, v154
	v_rcp_f32_e32 v155, v155
	v_rcp_f32_e32 v156, v156
	v_rcp_f32_e32 v157, v157
	v_rcp_f32_e32 v158, v158
	v_rcp_f32_e32 v159, v159
	v_rcp_f32_e32 v160, v160
	v_rcp_f32_e32 v161, v161
	v_pk_mul_f32 v[14:15], v[14:15], v[154:155]
	v_pk_mul_f32 v[16:17], v[16:17], v[156:157]
	v_pk_mul_f32 v[10:11], v[10:11], v[158:159]
	v_pk_mul_f32 v[12:13], v[12:13], v[160:161]
	v_add_f32_e32 v199, v199, v14
	v_add_f32_e32 v199, v199, v15
	v_add_f32_e32 v199, v199, v16
	v_add_f32_e32 v199, v199, v17
	v_add_f32_e32 v199, v199, v10
	v_add_f32_e32 v199, v199, v11
	v_add_f32_e32 v199, v199, v12
	v_add_f32_e32 v199, v199, v13
	v_fmac_f32_e32 v231, v14, v14
	v_fmac_f32_e32 v231, v15, v15
	v_fmac_f32_e32 v231, v16, v16
	v_fmac_f32_e32 v231, v17, v17
	v_fmac_f32_e32 v231, v10, v10
	v_fmac_f32_e32 v231, v11, v11
	v_fmac_f32_e32 v231, v12, v12
	v_fmac_f32_e32 v231, v13, v13
	v_cvt_pk_bf16_f32 v130, v14, v15
	v_cvt_pk_bf16_f32 v131, v16, v17
	v_cvt_pk_bf16_f32 v132, v10, v11
	v_cvt_pk_bf16_f32 v133, v12, v13
	ds_write_b16 v167, v130 offset:0
	ds_write_b16_d16_hi v167, v130 offset:32
	ds_write_b16 v167, v131 offset:64
	ds_write_b16_d16_hi v167, v131 offset:96
	ds_write_b16 v167, v132 offset:128
	ds_write_b16_d16_hi v167, v132 offset:160
	ds_write_b16 v167, v133 offset:192
	ds_write_b16_d16_hi v167, v133 offset:224
	v_pk_mul_f32 v[6:7], v[6:7], v[190:191] op_sel_hi:[1,0]
	v_pk_mul_f32 v[8:9], v[8:9], v[190:191] op_sel_hi:[1,0]
	v_pk_mul_f32 v[2:3], v[2:3], v[190:191] op_sel_hi:[1,0]
	v_pk_mul_f32 v[4:5], v[4:5], v[190:191] op_sel_hi:[1,0]
	v_pk_mul_f32 v[154:155], v[6:7], s[2:3] op_sel_hi:[1,0]
	v_pk_mul_f32 v[156:157], v[8:9], s[2:3] op_sel_hi:[1,0]
	v_pk_mul_f32 v[158:159], v[2:3], s[2:3] op_sel_hi:[1,0]
	v_pk_mul_f32 v[160:161], v[4:5], s[2:3] op_sel_hi:[1,0]
	v_pk_mul_f32 v[154:155], v[6:7], v[154:155]
	v_pk_mul_f32 v[156:157], v[8:9], v[156:157]
	v_pk_mul_f32 v[158:159], v[2:3], v[158:159]
	v_pk_mul_f32 v[160:161], v[4:5], v[160:161]
	v_pk_fma_f32 v[154:155], v[6:7], v[154:155], v[6:7]
	v_pk_fma_f32 v[156:157], v[8:9], v[156:157], v[8:9]
	v_pk_fma_f32 v[158:159], v[2:3], v[158:159], v[2:3]
	v_pk_fma_f32 v[160:161], v[4:5], v[160:161], v[4:5]
	v_pk_mul_f32 v[154:155], v[154:155], s[48:49] op_sel_hi:[1,0]
	v_pk_mul_f32 v[156:157], v[156:157], s[48:49] op_sel_hi:[1,0]
	v_pk_mul_f32 v[158:159], v[158:159], s[48:49] op_sel_hi:[1,0]
	v_pk_mul_f32 v[160:161], v[160:161], s[48:49] op_sel_hi:[1,0]
	v_pk_mul_f32 v[154:155], v[154:155], s[28:29] op_sel_hi:[1,0]
	v_pk_mul_f32 v[156:157], v[156:157], s[28:29] op_sel_hi:[1,0]
	v_pk_mul_f32 v[158:159], v[158:159], s[28:29] op_sel_hi:[1,0]
	v_pk_mul_f32 v[160:161], v[160:161], s[28:29] op_sel_hi:[1,0]
	v_exp_f32_e32 v154, v154
	v_exp_f32_e32 v155, v155
	v_exp_f32_e32 v156, v156
	v_exp_f32_e32 v157, v157
	v_exp_f32_e32 v158, v158
	v_exp_f32_e32 v159, v159
	v_exp_f32_e32 v160, v160
	v_exp_f32_e32 v161, v161
	v_pk_add_f32 v[154:155], v[154:155], s[0:1] op_sel_hi:[1,0]
	v_pk_add_f32 v[156:157], v[156:157], s[0:1] op_sel_hi:[1,0]
	v_pk_add_f32 v[158:159], v[158:159], s[0:1] op_sel_hi:[1,0]
	v_pk_add_f32 v[160:161], v[160:161], s[0:1] op_sel_hi:[1,0]
	v_rcp_f32_e32 v154, v154
	v_rcp_f32_e32 v155, v155
	v_rcp_f32_e32 v156, v156
	v_rcp_f32_e32 v157, v157
	v_rcp_f32_e32 v158, v158
	v_rcp_f32_e32 v159, v159
	v_rcp_f32_e32 v160, v160
	v_rcp_f32_e32 v161, v161
	v_pk_mul_f32 v[6:7], v[6:7], v[154:155]
	v_pk_mul_f32 v[8:9], v[8:9], v[156:157]
	v_pk_mul_f32 v[2:3], v[2:3], v[158:159]
	v_pk_mul_f32 v[4:5], v[4:5], v[160:161]
	v_add_f32_e32 v199, v199, v6
	v_add_f32_e32 v199, v199, v7
	v_add_f32_e32 v199, v199, v8
	v_add_f32_e32 v199, v199, v9
	v_add_f32_e32 v199, v199, v2
	v_add_f32_e32 v199, v199, v3
	v_add_f32_e32 v199, v199, v4
	v_add_f32_e32 v199, v199, v5
	v_fmac_f32_e32 v231, v6, v6
	v_fmac_f32_e32 v231, v7, v7
	v_fmac_f32_e32 v231, v8, v8
	v_fmac_f32_e32 v231, v9, v9
	v_fmac_f32_e32 v231, v2, v2
	v_fmac_f32_e32 v231, v3, v3
	v_fmac_f32_e32 v231, v4, v4
	v_fmac_f32_e32 v231, v5, v5
	v_cvt_pk_bf16_f32 v130, v6, v7
	v_cvt_pk_bf16_f32 v131, v8, v9
	v_cvt_pk_bf16_f32 v132, v2, v3
	v_cvt_pk_bf16_f32 v133, v4, v5
	ds_write_b16 v167, v130 offset:8192
	ds_write_b16_d16_hi v167, v130 offset:8224
	ds_write_b16 v167, v131 offset:8256
	ds_write_b16_d16_hi v167, v131 offset:8288
	ds_write_b16 v167, v132 offset:8320
	ds_write_b16_d16_hi v167, v132 offset:8352
	ds_write_b16 v167, v133 offset:8384
	ds_write_b16_d16_hi v167, v133 offset:8416
	s_waitcnt lgkmcnt(0)
	ds_read_b128 v[232:235], v168
	ds_read_b128 v[236:239], v168 offset:16
	s_waitcnt lgkmcnt(0)
	global_store_dwordx4 v165, v[232:235], s[44:45] offset:96
	global_store_dwordx4 v165, v[236:239], s[44:45] offset:112
	v_xor_b32_e32 v248, 16, v217
	v_xor_b32_e32 v249, 32, v217
	v_lshlrev_b32_e32 v248, 2, v248
	v_lshlrev_b32_e32 v249, 2, v249
	ds_bpermute_b32 v240, v248, v192
	ds_bpermute_b32 v241, v248, v193
	ds_bpermute_b32 v242, v248, v194
	ds_bpermute_b32 v243, v248, v195
	ds_bpermute_b32 v244, v248, v196
	ds_bpermute_b32 v245, v248, v197
	ds_bpermute_b32 v246, v248, v198
	ds_bpermute_b32 v247, v248, v199
	s_waitcnt lgkmcnt(0)
	v_add_f32_e32 v192, v192, v240
	v_add_f32_e32 v193, v193, v241
	v_add_f32_e32 v194, v194, v242
	v_add_f32_e32 v195, v195, v243
	v_add_f32_e32 v196, v196, v244
	v_add_f32_e32 v197, v197, v245
	v_add_f32_e32 v198, v198, v246
	v_add_f32_e32 v199, v199, v247
	ds_bpermute_b32 v240, v248, v224
	ds_bpermute_b32 v241, v248, v225
	ds_bpermute_b32 v242, v248, v226
	ds_bpermute_b32 v243, v248, v227
	ds_bpermute_b32 v244, v248, v228
	ds_bpermute_b32 v245, v248, v229
	ds_bpermute_b32 v246, v248, v230
	ds_bpermute_b32 v247, v248, v231
	s_waitcnt lgkmcnt(0)
	v_add_f32_e32 v224, v224, v240
	v_add_f32_e32 v225, v225, v241
	v_add_f32_e32 v226, v226, v242
	v_add_f32_e32 v227, v227, v243
	v_add_f32_e32 v228, v228, v244
	v_add_f32_e32 v229, v229, v245
	v_add_f32_e32 v230, v230, v246
	v_add_f32_e32 v231, v231, v247
	ds_bpermute_b32 v240, v249, v192
	ds_bpermute_b32 v241, v249, v193
	ds_bpermute_b32 v242, v249, v194
	ds_bpermute_b32 v243, v249, v195
	ds_bpermute_b32 v244, v249, v196
	ds_bpermute_b32 v245, v249, v197
	ds_bpermute_b32 v246, v249, v198
	ds_bpermute_b32 v247, v249, v199
	s_waitcnt lgkmcnt(0)
	v_add_f32_e32 v192, v192, v240
	v_add_f32_e32 v193, v193, v241
	v_add_f32_e32 v194, v194, v242
	v_add_f32_e32 v195, v195, v243
	v_add_f32_e32 v196, v196, v244
	v_add_f32_e32 v197, v197, v245
	v_add_f32_e32 v198, v198, v246
	v_add_f32_e32 v199, v199, v247
	ds_bpermute_b32 v240, v249, v224
	ds_bpermute_b32 v241, v249, v225
	ds_bpermute_b32 v242, v249, v226
	ds_bpermute_b32 v243, v249, v227
	ds_bpermute_b32 v244, v249, v228
	ds_bpermute_b32 v245, v249, v229
	ds_bpermute_b32 v246, v249, v230
	ds_bpermute_b32 v247, v249, v231
	s_waitcnt lgkmcnt(0)
	v_add_f32_e32 v224, v224, v240
	v_add_f32_e32 v225, v225, v241
	v_add_f32_e32 v226, v226, v242
	v_add_f32_e32 v227, v227, v243
	v_add_f32_e32 v228, v228, v244
	v_add_f32_e32 v229, v229, v245
	v_add_f32_e32 v230, v230, v246
	v_add_f32_e32 v231, v231, v247
	s_and_saveexec_b64 s[0:1], s[38:39]
	global_atomic_add_f32 v163, v192, s[10:11]
	global_atomic_add_f32 v163, v224, s[10:11] offset:4
	global_atomic_add_f32 v163, v193, s[10:11] offset:128
	global_atomic_add_f32 v163, v225, s[10:11] offset:132
	global_atomic_add_f32 v163, v194, s[10:11] offset:256
	global_atomic_add_f32 v163, v226, s[10:11] offset:260
	global_atomic_add_f32 v163, v195, s[10:11] offset:384
	global_atomic_add_f32 v163, v227, s[10:11] offset:388
	global_atomic_add_f32 v163, v196, s[10:11] offset:1024
	global_atomic_add_f32 v163, v228, s[10:11] offset:1028
	global_atomic_add_f32 v163, v197, s[10:11] offset:1152
	global_atomic_add_f32 v163, v229, s[10:11] offset:1156
	global_atomic_add_f32 v163, v198, s[10:11] offset:1280
	global_atomic_add_f32 v163, v230, s[10:11] offset:1284
	global_atomic_add_f32 v163, v199, s[10:11] offset:1408
	global_atomic_add_f32 v163, v231, s[10:11] offset:1412
	s_or_b64 exec, exec, s[0:1]
	s_branch .Lfe_done
.Lfe_kv:
	s_lshl_b32 s19, s42, 8
	s_add_i32 s19, s19, s71
	v_or_b32_e32 v162, s19, v147
	v_lshl_or_b32 v130, s35, 8, v174
	s_movk_i32 s27, 0x6a00
	ds_read_b32 v176, v172
	ds_read_b32 v178, v172 offset:64
	ds_read_b32 v180, v172 offset:128
	ds_read_b32 v182, v172 offset:192
	ds_read_b32 v184, v172 offset:512
	ds_read_b32 v186, v172 offset:576
	ds_read_b32 v188, v172 offset:640
	ds_read_b32 v190, v172 offset:704
	v_mul_u32_u24_e32 v165, s27, v162
	v_readlane_b32 s34, v251, 14
	v_readlane_b32 s35, v251, 15
	v_lshl_add_u32 v165, v130, 1, v165
	v_xor_b32_e32 v167, 16, v217
	v_lshlrev_b32_e32 v167, 2, v167
	v_add_u32_e32 v168, 0x20440, v170
	v_and_b32_e32 v169, 24, v174
	v_lshlrev_b32_e32 v169, 5, v169
	v_lshl_add_u32 v169, v147, 1, v169
	s_add_i32 s27, s67, 0xc000
	v_add_u32_e32 v169, s27, v169
	v_and_b32_e32 v163, 31, v217
	v_lshl_add_u32 v248, v163, 5, s27
	v_lshrrev_b32_e32 v249, 6, v174
	s_lshr_b32 s27, s42, 3
	v_lshl_add_u32 v249, s27, 1, v249
	v_lshlrev_b32_e32 v249, 6, v249
	v_and_b32_e32 v131, 32, v174
	v_add3_u32 v249, v249, v131, v163
	v_lshlrev_b32_e32 v249, 12, v249
	s_and_b32 s27, s42, 7
	s_lshl_b32 s27, s27, 9
	v_add_u32_e32 v249, s27, v249
	s_lshl_b32 s27, s71, 1
	v_add_u32_e32 v249, s27, v249
	v_readlane_b32 s44, v251, 18
	v_readlane_b32 s45, v251, 19
	s_waitcnt lgkmcnt(0)
	v_pk_mul_f32 v[126:127], v[126:127], v[176:177] op_sel_hi:[1,0]
	v_pk_mul_f32 v[128:129], v[128:129], v[176:177] op_sel_hi:[1,0]
	v_pk_mul_f32 v[122:123], v[122:123], v[176:177] op_sel_hi:[1,0]
	v_pk_mul_f32 v[124:125], v[124:125], v[176:177] op_sel_hi:[1,0]
	v_pk_mul_f32 v[118:119], v[118:119], v[176:177] op_sel_hi:[1,0]
	v_pk_mul_f32 v[120:121], v[120:121], v[176:177] op_sel_hi:[1,0]
	v_pk_mul_f32 v[114:115], v[114:115], v[176:177] op_sel_hi:[1,0]
	v_pk_mul_f32 v[116:117], v[116:117], v[176:177] op_sel_hi:[1,0]
	s_and_saveexec_b64 s[0:1], s[14:15]
	s_cbranch_execz .Lfe_kv_nr0
	ds_read_b128 v[232:235], v168 offset:0
	ds_read_b128 v[236:239], v168 offset:16
	ds_read_b128 v[240:243], v168 offset:32
	ds_read_b128 v[244:247], v168 offset:48
	s_mov_b64 exec, s[0:1]
	ds_bpermute_b32 v154, v167, v126
	ds_bpermute_b32 v155, v167, v127
	ds_bpermute_b32 v156, v167, v128
	ds_bpermute_b32 v157, v167, v129
	ds_bpermute_b32 v158, v167, v122
	ds_bpermute_b32 v159, v167, v123
	ds_bpermute_b32 v160, v167, v124
	ds_bpermute_b32 v161, v167, v125
	s_and_b64 exec, exec, s[14:15]
	s_waitcnt lgkmcnt(8)
	v_cndmask_b32_e64 v233, v233, -v233, s[38:39]
	v_cndmask_b32_e64 v235, v235, -v235, s[38:39]
	v_cndmask_b32_e64 v237, v237, -v237, s[38:39]
	v_cndmask_b32_e64 v239, v239, -v239, s[38:39]
	v_cndmask_b32_e64 v241, v241, -v241, s[38:39]
	v_cndmask_b32_e64 v243, v243, -v243, s[38:39]
	v_cndmask_b32_e64 v245, v245, -v245, s[38:39]
	v_cndmask_b32_e64 v247, v247, -v247, s[38:39]
	s_waitcnt lgkmcnt(0)
	v_mul_f32_e32 v224, v154, v233
	v_mul_f32_e32 v225, v155, v235
	v_mul_f32_e32 v226, v156, v237
	v_mul_f32_e32 v227, v157, v239
	v_mul_f32_e32 v228, v158, v241
	v_mul_f32_e32 v229, v159, v243
	v_mul_f32_e32 v230, v160, v245
	v_mul_f32_e32 v231, v161, v247
	v_fma_f32 v126, v126, v232, v224
	v_fma_f32 v127, v127, v234, v225
	v_fma_f32 v128, v128, v236, v226
	v_fma_f32 v129, v129, v238, v227
	v_fma_f32 v122, v122, v240, v228
	v_fma_f32 v123, v123, v242, v229
	v_fma_f32 v124, v124, v244, v230
	v_fma_f32 v125, v125, v246, v231
.Lfe_kv_nr0:
	s_or_b64 exec, exec, s[0:1]
	v_cvt_pk_bf16_f32 v130, v126, v127
	v_cvt_pk_bf16_f32 v131, v128, v129
	v_cvt_pk_bf16_f32 v132, v122, v123
	v_cvt_pk_bf16_f32 v133, v124, v125
	global_store_dwordx4 v165, v[130:133], s[34:35] nt
	v_cvt_pk_bf16_f32 v134, v118, v119
	v_cvt_pk_bf16_f32 v135, v120, v121
	v_cvt_pk_bf16_f32 v136, v114, v115
	v_cvt_pk_bf16_f32 v137, v116, v117
	ds_write_b16 v169, v134 offset:0
	ds_write_b16_d16_hi v169, v134 offset:32
	ds_write_b16 v169, v135 offset:64
	ds_write_b16_d16_hi v169, v135 offset:96
	ds_write_b16 v169, v136 offset:128
	ds_write_b16_d16_hi v169, v136 offset:160
	ds_write_b16 v169, v137 offset:192
	ds_write_b16_d16_hi v169, v137 offset:224
	s_waitcnt lgkmcnt(0)
	s_mov_b64 s[0:1], exec
	s_mov_b32 exec_hi, 0
	ds_read_b128 v[240:243], v248
	ds_read_b128 v[244:247], v248 offset:16
	s_waitcnt lgkmcnt(0)
	global_store_dwordx4 v249, v[240:243], s[44:45]
	global_store_dwordx4 v249, v[244:247], s[44:45] offset:16
	s_mov_b64 exec, s[0:1]
	v_add_u32_e32 v166, 0x6a000, v165
	v_pk_mul_f32 v[110:111], v[110:111], v[178:179] op_sel_hi:[1,0]
	v_pk_mul_f32 v[112:113], v[112:113], v[178:179] op_sel_hi:[1,0]
	v_pk_mul_f32 v[106:107], v[106:107], v[178:179] op_sel_hi:[1,0]
	v_pk_mul_f32 v[108:109], v[108:109], v[178:179] op_sel_hi:[1,0]
	v_pk_mul_f32 v[102:103], v[102:103], v[178:179] op_sel_hi:[1,0]
	v_pk_mul_f32 v[104:105], v[104:105], v[178:179] op_sel_hi:[1,0]
	v_pk_mul_f32 v[98:99], v[98:99], v[178:179] op_sel_hi:[1,0]
	v_pk_mul_f32 v[100:101], v[100:101], v[178:179] op_sel_hi:[1,0]
	s_and_saveexec_b64 s[0:1], s[14:15]
	s_cbranch_execz .Lfe_kv_nr1
	ds_read_b128 v[232:235], v168 offset:1024
	ds_read_b128 v[236:239], v168 offset:1040
	ds_read_b128 v[240:243], v168 offset:1056
	ds_read_b128 v[244:247], v168 offset:1072
	s_mov_b64 exec, s[0:1]
	ds_bpermute_b32 v154, v167, v110
	ds_bpermute_b32 v155, v167, v111
	ds_bpermute_b32 v156, v167, v112
	ds_bpermute_b32 v157, v167, v113
	ds_bpermute_b32 v158, v167, v106
	ds_bpermute_b32 v159, v167, v107
	ds_bpermute_b32 v160, v167, v108
	ds_bpermute_b32 v161, v167, v109
	s_and_b64 exec, exec, s[14:15]
	s_waitcnt lgkmcnt(8)
	v_cndmask_b32_e64 v233, v233, -v233, s[38:39]
	v_cndmask_b32_e64 v235, v235, -v235, s[38:39]
	v_cndmask_b32_e64 v237, v237, -v237, s[38:39]
	v_cndmask_b32_e64 v239, v239, -v239, s[38:39]
	v_cndmask_b32_e64 v241, v241, -v241, s[38:39]
	v_cndmask_b32_e64 v243, v243, -v243, s[38:39]
	v_cndmask_b32_e64 v245, v245, -v245, s[38:39]
	v_cndmask_b32_e64 v247, v247, -v247, s[38:39]
	s_waitcnt lgkmcnt(0)
	v_mul_f32_e32 v224, v154, v233
	v_mul_f32_e32 v225, v155, v235
	v_mul_f32_e32 v226, v156, v237
	v_mul_f32_e32 v227, v157, v239
	v_mul_f32_e32 v228, v158, v241
	v_mul_f32_e32 v229, v159, v243
	v_mul_f32_e32 v230, v160, v245
	v_mul_f32_e32 v231, v161, v247
	v_fma_f32 v110, v110, v232, v224
	v_fma_f32 v111, v111, v234, v225
	v_fma_f32 v112, v112, v236, v226
	v_fma_f32 v113, v113, v238, v227
	v_fma_f32 v106, v106, v240, v228
	v_fma_f32 v107, v107, v242, v229
	v_fma_f32 v108, v108, v244, v230
	v_fma_f32 v109, v109, v246, v231
.Lfe_kv_nr1:
	s_or_b64 exec, exec, s[0:1]
	v_cvt_pk_bf16_f32 v130, v110, v111
	v_cvt_pk_bf16_f32 v131, v112, v113
	v_cvt_pk_bf16_f32 v132, v106, v107
	v_cvt_pk_bf16_f32 v133, v108, v109
	global_store_dwordx4 v166, v[130:133], s[34:35] nt
	v_cvt_pk_bf16_f32 v134, v102, v103
	v_cvt_pk_bf16_f32 v135, v104, v105
	v_cvt_pk_bf16_f32 v136, v98, v99
	v_cvt_pk_bf16_f32 v137, v100, v101
	ds_write_b16 v169, v134 offset:0
	ds_write_b16_d16_hi v169, v134 offset:32
	ds_write_b16 v169, v135 offset:64
	ds_write_b16_d16_hi v169, v135 offset:96
	ds_write_b16 v169, v136 offset:128
	ds_write_b16_d16_hi v169, v136 offset:160
	ds_write_b16 v169, v137 offset:192
	ds_write_b16_d16_hi v169, v137 offset:224
	s_waitcnt lgkmcnt(0)
	s_mov_b64 s[0:1], exec
	s_mov_b32 exec_hi, 0
	ds_read_b128 v[240:243], v248
	ds_read_b128 v[244:247], v248 offset:16
	s_waitcnt lgkmcnt(0)
	global_store_dwordx4 v249, v[240:243], s[44:45] offset:32
	global_store_dwordx4 v249, v[244:247], s[44:45] offset:48
	s_mov_b64 exec, s[0:1]
	v_add_u32_e32 v164, 0xd4000, v165
	v_pk_mul_f32 v[94:95], v[94:95], v[180:181] op_sel_hi:[1,0]
	v_pk_mul_f32 v[96:97], v[96:97], v[180:181] op_sel_hi:[1,0]
	v_pk_mul_f32 v[90:91], v[90:91], v[180:181] op_sel_hi:[1,0]
	v_pk_mul_f32 v[92:93], v[92:93], v[180:181] op_sel_hi:[1,0]
	v_pk_mul_f32 v[86:87], v[86:87], v[180:181] op_sel_hi:[1,0]
	v_pk_mul_f32 v[88:89], v[88:89], v[180:181] op_sel_hi:[1,0]
	v_pk_mul_f32 v[82:83], v[82:83], v[180:181] op_sel_hi:[1,0]
	v_pk_mul_f32 v[84:85], v[84:85], v[180:181] op_sel_hi:[1,0]
	s_and_saveexec_b64 s[0:1], s[14:15]
	s_cbranch_execz .Lfe_kv_nr2
	ds_read_b128 v[232:235], v168 offset:2048
	ds_read_b128 v[236:239], v168 offset:2064
	ds_read_b128 v[240:243], v168 offset:2080
	ds_read_b128 v[244:247], v168 offset:2096
	s_mov_b64 exec, s[0:1]
	ds_bpermute_b32 v154, v167, v94
	ds_bpermute_b32 v155, v167, v95
	ds_bpermute_b32 v156, v167, v96
	ds_bpermute_b32 v157, v167, v97
	ds_bpermute_b32 v158, v167, v90
	ds_bpermute_b32 v159, v167, v91
	ds_bpermute_b32 v160, v167, v92
	ds_bpermute_b32 v161, v167, v93
	s_and_b64 exec, exec, s[14:15]
	s_waitcnt lgkmcnt(8)
	v_cndmask_b32_e64 v233, v233, -v233, s[38:39]
	v_cndmask_b32_e64 v235, v235, -v235, s[38:39]
	v_cndmask_b32_e64 v237, v237, -v237, s[38:39]
	v_cndmask_b32_e64 v239, v239, -v239, s[38:39]
	v_cndmask_b32_e64 v241, v241, -v241, s[38:39]
	v_cndmask_b32_e64 v243, v243, -v243, s[38:39]
	v_cndmask_b32_e64 v245, v245, -v245, s[38:39]
	v_cndmask_b32_e64 v247, v247, -v247, s[38:39]
	s_waitcnt lgkmcnt(0)
	v_mul_f32_e32 v224, v154, v233
	v_mul_f32_e32 v225, v155, v235
	v_mul_f32_e32 v226, v156, v237
	v_mul_f32_e32 v227, v157, v239
	v_mul_f32_e32 v228, v158, v241
	v_mul_f32_e32 v229, v159, v243
	v_mul_f32_e32 v230, v160, v245
	v_mul_f32_e32 v231, v161, v247
	v_fma_f32 v94, v94, v232, v224
	v_fma_f32 v95, v95, v234, v225
	v_fma_f32 v96, v96, v236, v226
	v_fma_f32 v97, v97, v238, v227
	v_fma_f32 v90, v90, v240, v228
	v_fma_f32 v91, v91, v242, v229
	v_fma_f32 v92, v92, v244, v230
	v_fma_f32 v93, v93, v246, v231
.Lfe_kv_nr2:
	s_or_b64 exec, exec, s[0:1]
	v_cvt_pk_bf16_f32 v130, v94, v95
	v_cvt_pk_bf16_f32 v131, v96, v97
	v_cvt_pk_bf16_f32 v132, v90, v91
	v_cvt_pk_bf16_f32 v133, v92, v93
	global_store_dwordx4 v164, v[130:133], s[34:35] nt
	v_cvt_pk_bf16_f32 v134, v86, v87
	v_cvt_pk_bf16_f32 v135, v88, v89
	v_cvt_pk_bf16_f32 v136, v82, v83
	v_cvt_pk_bf16_f32 v137, v84, v85
	ds_write_b16 v169, v134 offset:0
	ds_write_b16_d16_hi v169, v134 offset:32
	ds_write_b16 v169, v135 offset:64
	ds_write_b16_d16_hi v169, v135 offset:96
	ds_write_b16 v169, v136 offset:128
	ds_write_b16_d16_hi v169, v136 offset:160
	ds_write_b16 v169, v137 offset:192
	ds_write_b16_d16_hi v169, v137 offset:224
	s_waitcnt lgkmcnt(0)
	s_mov_b64 s[0:1], exec
	s_mov_b32 exec_hi, 0
	ds_read_b128 v[240:243], v248
	ds_read_b128 v[244:247], v248 offset:16
	s_waitcnt lgkmcnt(0)
	global_store_dwordx4 v249, v[240:243], s[44:45] offset:64
	global_store_dwordx4 v249, v[244:247], s[44:45] offset:80
	s_mov_b64 exec, s[0:1]
	v_add_u32_e32 v166, 0x13e000, v165
	v_pk_mul_f32 v[78:79], v[78:79], v[182:183] op_sel_hi:[1,0]
	v_pk_mul_f32 v[80:81], v[80:81], v[182:183] op_sel_hi:[1,0]
	v_pk_mul_f32 v[74:75], v[74:75], v[182:183] op_sel_hi:[1,0]
	v_pk_mul_f32 v[76:77], v[76:77], v[182:183] op_sel_hi:[1,0]
	v_pk_mul_f32 v[70:71], v[70:71], v[182:183] op_sel_hi:[1,0]
	v_pk_mul_f32 v[72:73], v[72:73], v[182:183] op_sel_hi:[1,0]
	v_pk_mul_f32 v[66:67], v[66:67], v[182:183] op_sel_hi:[1,0]
	v_pk_mul_f32 v[68:69], v[68:69], v[182:183] op_sel_hi:[1,0]
	s_and_saveexec_b64 s[0:1], s[14:15]
	s_cbranch_execz .Lfe_kv_nr3
	ds_read_b128 v[232:235], v168 offset:3072
	ds_read_b128 v[236:239], v168 offset:3088
	ds_read_b128 v[240:243], v168 offset:3104
	ds_read_b128 v[244:247], v168 offset:3120
	s_mov_b64 exec, s[0:1]
	ds_bpermute_b32 v154, v167, v78
	ds_bpermute_b32 v155, v167, v79
	ds_bpermute_b32 v156, v167, v80
	ds_bpermute_b32 v157, v167, v81
	ds_bpermute_b32 v158, v167, v74
	ds_bpermute_b32 v159, v167, v75
	ds_bpermute_b32 v160, v167, v76
	ds_bpermute_b32 v161, v167, v77
	s_and_b64 exec, exec, s[14:15]
	s_waitcnt lgkmcnt(8)
	v_cndmask_b32_e64 v233, v233, -v233, s[38:39]
	v_cndmask_b32_e64 v235, v235, -v235, s[38:39]
	v_cndmask_b32_e64 v237, v237, -v237, s[38:39]
	v_cndmask_b32_e64 v239, v239, -v239, s[38:39]
	v_cndmask_b32_e64 v241, v241, -v241, s[38:39]
	v_cndmask_b32_e64 v243, v243, -v243, s[38:39]
	v_cndmask_b32_e64 v245, v245, -v245, s[38:39]
	v_cndmask_b32_e64 v247, v247, -v247, s[38:39]
	s_waitcnt lgkmcnt(0)
	v_mul_f32_e32 v224, v154, v233
	v_mul_f32_e32 v225, v155, v235
	v_mul_f32_e32 v226, v156, v237
	v_mul_f32_e32 v227, v157, v239
	v_mul_f32_e32 v228, v158, v241
	v_mul_f32_e32 v229, v159, v243
	v_mul_f32_e32 v230, v160, v245
	v_mul_f32_e32 v231, v161, v247
	v_fma_f32 v78, v78, v232, v224
	v_fma_f32 v79, v79, v234, v225
	v_fma_f32 v80, v80, v236, v226
	v_fma_f32 v81, v81, v238, v227
	v_fma_f32 v74, v74, v240, v228
	v_fma_f32 v75, v75, v242, v229
	v_fma_f32 v76, v76, v244, v230
	v_fma_f32 v77, v77, v246, v231
.Lfe_kv_nr3:
	s_or_b64 exec, exec, s[0:1]
	v_cvt_pk_bf16_f32 v130, v78, v79
	v_cvt_pk_bf16_f32 v131, v80, v81
	v_cvt_pk_bf16_f32 v132, v74, v75
	v_cvt_pk_bf16_f32 v133, v76, v77
	global_store_dwordx4 v166, v[130:133], s[34:35] nt
	v_cvt_pk_bf16_f32 v134, v70, v71
	v_cvt_pk_bf16_f32 v135, v72, v73
	v_cvt_pk_bf16_f32 v136, v66, v67
	v_cvt_pk_bf16_f32 v137, v68, v69
	ds_write_b16 v169, v134 offset:0
	ds_write_b16_d16_hi v169, v134 offset:32
	ds_write_b16 v169, v135 offset:64
	ds_write_b16_d16_hi v169, v135 offset:96
	ds_write_b16 v169, v136 offset:128
	ds_write_b16_d16_hi v169, v136 offset:160
	ds_write_b16 v169, v137 offset:192
	ds_write_b16_d16_hi v169, v137 offset:224
	s_waitcnt lgkmcnt(0)
	s_mov_b64 s[0:1], exec
	s_mov_b32 exec_hi, 0
	ds_read_b128 v[240:243], v248
	ds_read_b128 v[244:247], v248 offset:16
	s_waitcnt lgkmcnt(0)
	global_store_dwordx4 v249, v[240:243], s[44:45] offset:96
	global_store_dwordx4 v249, v[244:247], s[44:45] offset:112
	s_mov_b64 exec, s[0:1]
	v_add_u32_e32 v164, 0x350000, v165
	v_pk_mul_f32 v[62:63], v[62:63], v[184:185] op_sel_hi:[1,0]
	v_pk_mul_f32 v[64:65], v[64:65], v[184:185] op_sel_hi:[1,0]
	v_pk_mul_f32 v[58:59], v[58:59], v[184:185] op_sel_hi:[1,0]
	v_pk_mul_f32 v[60:61], v[60:61], v[184:185] op_sel_hi:[1,0]
	v_pk_mul_f32 v[54:55], v[54:55], v[184:185] op_sel_hi:[1,0]
	v_pk_mul_f32 v[56:57], v[56:57], v[184:185] op_sel_hi:[1,0]
	v_pk_mul_f32 v[50:51], v[50:51], v[184:185] op_sel_hi:[1,0]
	v_pk_mul_f32 v[52:53], v[52:53], v[184:185] op_sel_hi:[1,0]
	s_and_saveexec_b64 s[0:1], s[14:15]
	s_cbranch_execz .Lfe_kv_nr4
	ds_read_b128 v[232:235], v168 offset:8192
	ds_read_b128 v[236:239], v168 offset:8208
	ds_read_b128 v[240:243], v168 offset:8224
	ds_read_b128 v[244:247], v168 offset:8240
	s_mov_b64 exec, s[0:1]
	ds_bpermute_b32 v154, v167, v62
	ds_bpermute_b32 v155, v167, v63
	ds_bpermute_b32 v156, v167, v64
	ds_bpermute_b32 v157, v167, v65
	ds_bpermute_b32 v158, v167, v58
	ds_bpermute_b32 v159, v167, v59
	ds_bpermute_b32 v160, v167, v60
	ds_bpermute_b32 v161, v167, v61
	s_and_b64 exec, exec, s[14:15]
	s_waitcnt lgkmcnt(8)
	v_cndmask_b32_e64 v233, v233, -v233, s[38:39]
	v_cndmask_b32_e64 v235, v235, -v235, s[38:39]
	v_cndmask_b32_e64 v237, v237, -v237, s[38:39]
	v_cndmask_b32_e64 v239, v239, -v239, s[38:39]
	v_cndmask_b32_e64 v241, v241, -v241, s[38:39]
	v_cndmask_b32_e64 v243, v243, -v243, s[38:39]
	v_cndmask_b32_e64 v245, v245, -v245, s[38:39]
	v_cndmask_b32_e64 v247, v247, -v247, s[38:39]
	s_waitcnt lgkmcnt(0)
	v_mul_f32_e32 v224, v154, v233
	v_mul_f32_e32 v225, v155, v235
	v_mul_f32_e32 v226, v156, v237
	v_mul_f32_e32 v227, v157, v239
	v_mul_f32_e32 v228, v158, v241
	v_mul_f32_e32 v229, v159, v243
	v_mul_f32_e32 v230, v160, v245
	v_mul_f32_e32 v231, v161, v247
	v_fma_f32 v62, v62, v232, v224
	v_fma_f32 v63, v63, v234, v225
	v_fma_f32 v64, v64, v236, v226
	v_fma_f32 v65, v65, v238, v227
	v_fma_f32 v58, v58, v240, v228
	v_fma_f32 v59, v59, v242, v229
	v_fma_f32 v60, v60, v244, v230
	v_fma_f32 v61, v61, v246, v231
.Lfe_kv_nr4:
	s_or_b64 exec, exec, s[0:1]
	v_cvt_pk_bf16_f32 v130, v62, v63
	v_cvt_pk_bf16_f32 v131, v64, v65
	v_cvt_pk_bf16_f32 v132, v58, v59
	v_cvt_pk_bf16_f32 v133, v60, v61
	global_store_dwordx4 v164, v[130:133], s[34:35] nt
	v_cvt_pk_bf16_f32 v134, v54, v55
	v_cvt_pk_bf16_f32 v135, v56, v57
	v_cvt_pk_bf16_f32 v136, v50, v51
	v_cvt_pk_bf16_f32 v137, v52, v53
	ds_write_b16 v169, v134 offset:0
	ds_write_b16_d16_hi v169, v134 offset:32
	ds_write_b16 v169, v135 offset:64
	ds_write_b16_d16_hi v169, v135 offset:96
	ds_write_b16 v169, v136 offset:128
	ds_write_b16_d16_hi v169, v136 offset:160
	ds_write_b16 v169, v137 offset:192
	ds_write_b16_d16_hi v169, v137 offset:224
	s_waitcnt lgkmcnt(0)
	s_mov_b64 s[0:1], exec
	s_mov_b32 exec_hi, 0
	ds_read_b128 v[240:243], v248
	ds_read_b128 v[244:247], v248 offset:16
	s_waitcnt lgkmcnt(0)
	global_store_dwordx4 v249, v[240:243], s[44:45] offset:256
	global_store_dwordx4 v249, v[244:247], s[44:45] offset:272
	s_mov_b64 exec, s[0:1]
	v_add_u32_e32 v166, 0x3ba000, v165
	v_pk_mul_f32 v[46:47], v[46:47], v[186:187] op_sel_hi:[1,0]
	v_pk_mul_f32 v[48:49], v[48:49], v[186:187] op_sel_hi:[1,0]
	v_pk_mul_f32 v[42:43], v[42:43], v[186:187] op_sel_hi:[1,0]
	v_pk_mul_f32 v[44:45], v[44:45], v[186:187] op_sel_hi:[1,0]
	v_pk_mul_f32 v[38:39], v[38:39], v[186:187] op_sel_hi:[1,0]
	v_pk_mul_f32 v[40:41], v[40:41], v[186:187] op_sel_hi:[1,0]
	v_pk_mul_f32 v[34:35], v[34:35], v[186:187] op_sel_hi:[1,0]
	v_pk_mul_f32 v[36:37], v[36:37], v[186:187] op_sel_hi:[1,0]
	s_and_saveexec_b64 s[0:1], s[14:15]
	s_cbranch_execz .Lfe_kv_nr5
	ds_read_b128 v[232:235], v168 offset:9216
	ds_read_b128 v[236:239], v168 offset:9232
	ds_read_b128 v[240:243], v168 offset:9248
	ds_read_b128 v[244:247], v168 offset:9264
	s_mov_b64 exec, s[0:1]
	ds_bpermute_b32 v154, v167, v46
	ds_bpermute_b32 v155, v167, v47
	ds_bpermute_b32 v156, v167, v48
	ds_bpermute_b32 v157, v167, v49
	ds_bpermute_b32 v158, v167, v42
	ds_bpermute_b32 v159, v167, v43
	ds_bpermute_b32 v160, v167, v44
	ds_bpermute_b32 v161, v167, v45
	s_and_b64 exec, exec, s[14:15]
	s_waitcnt lgkmcnt(8)
	v_cndmask_b32_e64 v233, v233, -v233, s[38:39]
	v_cndmask_b32_e64 v235, v235, -v235, s[38:39]
	v_cndmask_b32_e64 v237, v237, -v237, s[38:39]
	v_cndmask_b32_e64 v239, v239, -v239, s[38:39]
	v_cndmask_b32_e64 v241, v241, -v241, s[38:39]
	v_cndmask_b32_e64 v243, v243, -v243, s[38:39]
	v_cndmask_b32_e64 v245, v245, -v245, s[38:39]
	v_cndmask_b32_e64 v247, v247, -v247, s[38:39]
	s_waitcnt lgkmcnt(0)
	v_mul_f32_e32 v224, v154, v233
	v_mul_f32_e32 v225, v155, v235
	v_mul_f32_e32 v226, v156, v237
	v_mul_f32_e32 v227, v157, v239
	v_mul_f32_e32 v228, v158, v241
	v_mul_f32_e32 v229, v159, v243
	v_mul_f32_e32 v230, v160, v245
	v_mul_f32_e32 v231, v161, v247
	v_fma_f32 v46, v46, v232, v224
	v_fma_f32 v47, v47, v234, v225
	v_fma_f32 v48, v48, v236, v226
	v_fma_f32 v49, v49, v238, v227
	v_fma_f32 v42, v42, v240, v228
	v_fma_f32 v43, v43, v242, v229
	v_fma_f32 v44, v44, v244, v230
	v_fma_f32 v45, v45, v246, v231
.Lfe_kv_nr5:
	s_or_b64 exec, exec, s[0:1]
	v_cvt_pk_bf16_f32 v130, v46, v47
	v_cvt_pk_bf16_f32 v131, v48, v49
	v_cvt_pk_bf16_f32 v132, v42, v43
	v_cvt_pk_bf16_f32 v133, v44, v45
	global_store_dwordx4 v166, v[130:133], s[34:35] nt
	v_cvt_pk_bf16_f32 v134, v38, v39
	v_cvt_pk_bf16_f32 v135, v40, v41
	v_cvt_pk_bf16_f32 v136, v34, v35
	v_cvt_pk_bf16_f32 v137, v36, v37
	ds_write_b16 v169, v134 offset:0
	ds_write_b16_d16_hi v169, v134 offset:32
	ds_write_b16 v169, v135 offset:64
	ds_write_b16_d16_hi v169, v135 offset:96
	ds_write_b16 v169, v136 offset:128
	ds_write_b16_d16_hi v169, v136 offset:160
	ds_write_b16 v169, v137 offset:192
	ds_write_b16_d16_hi v169, v137 offset:224
	s_waitcnt lgkmcnt(0)
	s_mov_b64 s[0:1], exec
	s_mov_b32 exec_hi, 0
	ds_read_b128 v[240:243], v248
	ds_read_b128 v[244:247], v248 offset:16
	s_waitcnt lgkmcnt(0)
	global_store_dwordx4 v249, v[240:243], s[44:45] offset:288
	global_store_dwordx4 v249, v[244:247], s[44:45] offset:304
	s_mov_b64 exec, s[0:1]
	v_add_u32_e32 v164, 0x424000, v165
	v_pk_mul_f32 v[30:31], v[30:31], v[188:189] op_sel_hi:[1,0]
	v_pk_mul_f32 v[32:33], v[32:33], v[188:189] op_sel_hi:[1,0]
	v_pk_mul_f32 v[26:27], v[26:27], v[188:189] op_sel_hi:[1,0]
	v_pk_mul_f32 v[28:29], v[28:29], v[188:189] op_sel_hi:[1,0]
	v_pk_mul_f32 v[22:23], v[22:23], v[188:189] op_sel_hi:[1,0]
	v_pk_mul_f32 v[24:25], v[24:25], v[188:189] op_sel_hi:[1,0]
	v_pk_mul_f32 v[18:19], v[18:19], v[188:189] op_sel_hi:[1,0]
	v_pk_mul_f32 v[20:21], v[20:21], v[188:189] op_sel_hi:[1,0]
	s_and_saveexec_b64 s[0:1], s[14:15]
	s_cbranch_execz .Lfe_kv_nr6
	ds_read_b128 v[232:235], v168 offset:10240
	ds_read_b128 v[236:239], v168 offset:10256
	ds_read_b128 v[240:243], v168 offset:10272
	ds_read_b128 v[244:247], v168 offset:10288
	s_mov_b64 exec, s[0:1]
	ds_bpermute_b32 v154, v167, v30
	ds_bpermute_b32 v155, v167, v31
	ds_bpermute_b32 v156, v167, v32
	ds_bpermute_b32 v157, v167, v33
	ds_bpermute_b32 v158, v167, v26
	ds_bpermute_b32 v159, v167, v27
	ds_bpermute_b32 v160, v167, v28
	ds_bpermute_b32 v161, v167, v29
	s_and_b64 exec, exec, s[14:15]
	s_waitcnt lgkmcnt(8)
	v_cndmask_b32_e64 v233, v233, -v233, s[38:39]
	v_cndmask_b32_e64 v235, v235, -v235, s[38:39]
	v_cndmask_b32_e64 v237, v237, -v237, s[38:39]
	v_cndmask_b32_e64 v239, v239, -v239, s[38:39]
	v_cndmask_b32_e64 v241, v241, -v241, s[38:39]
	v_cndmask_b32_e64 v243, v243, -v243, s[38:39]
	v_cndmask_b32_e64 v245, v245, -v245, s[38:39]
	v_cndmask_b32_e64 v247, v247, -v247, s[38:39]
	s_waitcnt lgkmcnt(0)
	v_mul_f32_e32 v224, v154, v233
	v_mul_f32_e32 v225, v155, v235
	v_mul_f32_e32 v226, v156, v237
	v_mul_f32_e32 v227, v157, v239
	v_mul_f32_e32 v228, v158, v241
	v_mul_f32_e32 v229, v159, v243
	v_mul_f32_e32 v230, v160, v245
	v_mul_f32_e32 v231, v161, v247
	v_fma_f32 v30, v30, v232, v224
	v_fma_f32 v31, v31, v234, v225
	v_fma_f32 v32, v32, v236, v226
	v_fma_f32 v33, v33, v238, v227
	v_fma_f32 v26, v26, v240, v228
	v_fma_f32 v27, v27, v242, v229
	v_fma_f32 v28, v28, v244, v230
	v_fma_f32 v29, v29, v246, v231
.Lfe_kv_nr6:
	s_or_b64 exec, exec, s[0:1]
	v_cvt_pk_bf16_f32 v130, v30, v31
	v_cvt_pk_bf16_f32 v131, v32, v33
	v_cvt_pk_bf16_f32 v132, v26, v27
	v_cvt_pk_bf16_f32 v133, v28, v29
	global_store_dwordx4 v164, v[130:133], s[34:35] nt
	v_cvt_pk_bf16_f32 v134, v22, v23
	v_cvt_pk_bf16_f32 v135, v24, v25
	v_cvt_pk_bf16_f32 v136, v18, v19
	v_cvt_pk_bf16_f32 v137, v20, v21
	ds_write_b16 v169, v134 offset:0
	ds_write_b16_d16_hi v169, v134 offset:32
	ds_write_b16 v169, v135 offset:64
	ds_write_b16_d16_hi v169, v135 offset:96
	ds_write_b16 v169, v136 offset:128
	ds_write_b16_d16_hi v169, v136 offset:160
	ds_write_b16 v169, v137 offset:192
	ds_write_b16_d16_hi v169, v137 offset:224
	s_waitcnt lgkmcnt(0)
	s_mov_b64 s[0:1], exec
	s_mov_b32 exec_hi, 0
	ds_read_b128 v[240:243], v248
	ds_read_b128 v[244:247], v248 offset:16
	s_waitcnt lgkmcnt(0)
	global_store_dwordx4 v249, v[240:243], s[44:45] offset:320
	global_store_dwordx4 v249, v[244:247], s[44:45] offset:336
	s_mov_b64 exec, s[0:1]
	v_add_u32_e32 v166, 0x48e000, v165
	v_pk_mul_f32 v[14:15], v[14:15], v[190:191] op_sel_hi:[1,0]
	v_pk_mul_f32 v[16:17], v[16:17], v[190:191] op_sel_hi:[1,0]
	v_pk_mul_f32 v[10:11], v[10:11], v[190:191] op_sel_hi:[1,0]
	v_pk_mul_f32 v[12:13], v[12:13], v[190:191] op_sel_hi:[1,0]
	v_pk_mul_f32 v[6:7], v[6:7], v[190:191] op_sel_hi:[1,0]
	v_pk_mul_f32 v[8:9], v[8:9], v[190:191] op_sel_hi:[1,0]
	v_pk_mul_f32 v[2:3], v[2:3], v[190:191] op_sel_hi:[1,0]
	v_pk_mul_f32 v[4:5], v[4:5], v[190:191] op_sel_hi:[1,0]
	s_and_saveexec_b64 s[0:1], s[14:15]
	s_cbranch_execz .Lfe_kv_nr7
	ds_read_b128 v[232:235], v168 offset:11264
	ds_read_b128 v[236:239], v168 offset:11280
	ds_read_b128 v[240:243], v168 offset:11296
	ds_read_b128 v[244:247], v168 offset:11312
	s_mov_b64 exec, s[0:1]
	ds_bpermute_b32 v154, v167, v14
	ds_bpermute_b32 v155, v167, v15
	ds_bpermute_b32 v156, v167, v16
	ds_bpermute_b32 v157, v167, v17
	ds_bpermute_b32 v158, v167, v10
	ds_bpermute_b32 v159, v167, v11
	ds_bpermute_b32 v160, v167, v12
	ds_bpermute_b32 v161, v167, v13
	s_and_b64 exec, exec, s[14:15]
	s_waitcnt lgkmcnt(8)
	v_cndmask_b32_e64 v233, v233, -v233, s[38:39]
	v_cndmask_b32_e64 v235, v235, -v235, s[38:39]
	v_cndmask_b32_e64 v237, v237, -v237, s[38:39]
	v_cndmask_b32_e64 v239, v239, -v239, s[38:39]
	v_cndmask_b32_e64 v241, v241, -v241, s[38:39]
	v_cndmask_b32_e64 v243, v243, -v243, s[38:39]
	v_cndmask_b32_e64 v245, v245, -v245, s[38:39]
	v_cndmask_b32_e64 v247, v247, -v247, s[38:39]
	s_waitcnt lgkmcnt(0)
	v_mul_f32_e32 v224, v154, v233
	v_mul_f32_e32 v225, v155, v235
	v_mul_f32_e32 v226, v156, v237
	v_mul_f32_e32 v227, v157, v239
	v_mul_f32_e32 v228, v158, v241
	v_mul_f32_e32 v229, v159, v243
	v_mul_f32_e32 v230, v160, v245
	v_mul_f32_e32 v231, v161, v247
	v_fma_f32 v14, v14, v232, v224
	v_fma_f32 v15, v15, v234, v225
	v_fma_f32 v16, v16, v236, v226
	v_fma_f32 v17, v17, v238, v227
	v_fma_f32 v10, v10, v240, v228
	v_fma_f32 v11, v11, v242, v229
	v_fma_f32 v12, v12, v244, v230
	v_fma_f32 v13, v13, v246, v231
.Lfe_kv_nr7:
	s_or_b64 exec, exec, s[0:1]
	v_cvt_pk_bf16_f32 v130, v14, v15
	v_cvt_pk_bf16_f32 v131, v16, v17
	v_cvt_pk_bf16_f32 v132, v10, v11
	v_cvt_pk_bf16_f32 v133, v12, v13
	global_store_dwordx4 v166, v[130:133], s[34:35] nt
	v_cvt_pk_bf16_f32 v134, v6, v7
	v_cvt_pk_bf16_f32 v135, v8, v9
	v_cvt_pk_bf16_f32 v136, v2, v3
	v_cvt_pk_bf16_f32 v137, v4, v5
	ds_write_b16 v169, v134 offset:0
	ds_write_b16_d16_hi v169, v134 offset:32
	ds_write_b16 v169, v135 offset:64
	ds_write_b16_d16_hi v169, v135 offset:96
	ds_write_b16 v169, v136 offset:128
	ds_write_b16_d16_hi v169, v136 offset:160
	ds_write_b16 v169, v137 offset:192
	ds_write_b16_d16_hi v169, v137 offset:224
	s_waitcnt lgkmcnt(0)
	s_mov_b64 s[0:1], exec
	s_mov_b32 exec_hi, 0
	ds_read_b128 v[240:243], v248
	ds_read_b128 v[244:247], v248 offset:16
	s_waitcnt lgkmcnt(0)
	global_store_dwordx4 v249, v[240:243], s[44:45] offset:352
	global_store_dwordx4 v249, v[244:247], s[44:45] offset:368
	s_mov_b64 exec, s[0:1]
	s_branch .Lfe_done
